# v22 + nt hint on recur2 (hgrn_pass2/ssd_pass2) dwordx4 tile/state loads (last-use reads of PROJ/xbcc/segment states)
# baseline (speedup 1.0000x reference)
; #define LAUNDER_PTR(p) do {} while (0)
; #define LAUNDER_PTR(p) asm volatile("" : "+v"(p))
; __device__ __forceinline__ void hgrn_pass2(const RecurBufs& rb, const float* hgn_l, float* state_out_l, int u, int tid, LAS unsigned char* lds) {
;     ...
;     {
;         f32x4 L[3][8], dcs[3];
; #pragma unroll
;         for (int s = 0; s < 3; ++s) if (s < seg) { const int u2 = u - seg + s;
;             dcs[s] = *(const f32x4*)(rb.dseg + u2 * 128 + 16 * w + 4 * g);
;             const float* sp = rb.sseg + (size_t)u2 * 16384 + tid * 4;
; #pragma unroll
;             for (int et = 0; et < 8; ++et) { LAUNDER_PTR(sp); L[s][et] = *(const f32x4*)sp; sp += 2048; } }
.LBB0_804:
	v_mov_b32_e32 v112, v137
	s_and_b32 s8, s69, 3
	v_ashrrev_i32_e32 v123, 6, v112
	s_and_b32 s6, s69, -4
	v_lshrrev_b32_e32 v0, 2, v112
	v_lshlrev_b32_e32 v114, 4, v123
	v_and_b32_e32 v122, 12, v0
	v_lshlrev_b32_e32 v116, 2, v112
	s_cmp_lg_u32 s8, 0
	v_ashrrev_i32_e32 v115, 31, v114
	v_ashrrev_i32_e32 v117, 31, v116
	s_cselect_b64 s[4:5], -1, 0
	s_cmp_eq_u32 s8, 0
	v_lshlrev_b32_e32 v8, 2, v122
	s_cbranch_scc1 .LBB0_846
	s_lshl_b32 s2, s6, 7
	s_ashr_i32 s3, s2, 31
	s_lshl_b64 s[2:3], s[2:3], 2
	s_add_u32 s2, s66, s2
	s_addc_u32 s3, s67, s3
	s_ashr_i32 s7, s6, 31
	v_lshl_add_u64 v[0:1], v[114:115], 2, s[2:3]
	s_lshl_b64 s[2:3], s[6:7], 16
	v_mov_b32_e32 v9, v11
	s_add_u32 s2, s62, s2
	v_lshl_add_u64 v[0:1], v[0:1], 0, v[8:9]
	s_addc_u32 s3, s63, s3
	global_load_dwordx4 v[16:19], v[0:1], off nt
	v_lshl_add_u64 v[0:1], v[116:117], 2, s[2:3]
	global_load_dwordx4 v[12:15], v[0:1], off nt
	v_lshl_add_u64 v[4:5], v[0:1], 0, s[44:45]
	global_load_dwordx4 v[0:3], v[4:5], off nt
	v_lshl_add_u64 v[4:5], v[4:5], 0, s[44:45]
	global_load_dwordx4 v[24:27], v[4:5], off nt
	v_lshl_add_u64 v[20:21], v[4:5], 0, s[44:45]
	global_load_dwordx4 v[4:7], v[20:21], off nt
	v_lshl_add_u64 v[20:21], v[20:21], 0, s[44:45]
	global_load_dwordx4 v[44:47], v[20:21], off nt
	v_lshl_add_u64 v[20:21], v[20:21], 0, s[44:45]
	global_load_dwordx4 v[52:55], v[20:21], off nt
	v_lshl_add_u64 v[20:21], v[20:21], 0, s[44:45]
	global_load_dwordx4 v[60:63], v[20:21], off nt
	v_lshl_add_u64 v[20:21], v[20:21], 0, s[44:45]
	global_load_dwordx4 v[108:111], v[20:21], off nt
	s_waitcnt vmcnt(0) lgkmcnt(0)
	v_pk_mul_f32 v[120:121], v[18:19], 0 op_sel_hi:[1,0]
	v_pk_mul_f32 v[118:119], v[16:17], 0 op_sel_hi:[1,0]
	s_cmp_gt_u32 s8, 1
	s_cselect_b64 s[2:3], -1, 0
	s_cmp_lt_u32 s8, 2
	s_cbranch_scc1 .LBB0_807
.LBB0_806:
	s_or_b32 s10, s6, 1
	s_lshl_b32 s12, s10, 7
	s_ashr_i32 s13, s12, 31
	s_lshl_b64 s[12:13], s[12:13], 2
	s_add_u32 s12, s66, s12
	s_addc_u32 s13, s67, s13
	s_ashr_i32 s11, s10, 31
	s_lshl_b64 s[10:11], s[10:11], 16
	v_lshl_add_u64 v[16:17], v[114:115], 2, s[12:13]
	v_mov_b32_e32 v9, v11
	s_add_u32 s10, s62, s10
	v_lshl_add_u64 v[16:17], v[16:17], 0, v[8:9]
	s_addc_u32 s11, s63, s11
	global_load_dwordx4 v[48:51], v[16:17], off nt
	v_lshl_add_u64 v[16:17], v[116:117], 2, s[10:11]
	global_load_dwordx4 v[104:107], v[16:17], off nt
	v_lshl_add_u64 v[16:17], v[16:17], 0, s[44:45]
	global_load_dwordx4 v[100:103], v[16:17], off nt
	v_lshl_add_u64 v[16:17], v[16:17], 0, s[44:45]
	global_load_dwordx4 v[96:99], v[16:17], off nt
	v_lshl_add_u64 v[16:17], v[16:17], 0, s[44:45]
	global_load_dwordx4 v[92:95], v[16:17], off nt
	v_lshl_add_u64 v[16:17], v[16:17], 0, s[44:45]
	global_load_dwordx4 v[88:91], v[16:17], off nt
	v_lshl_add_u64 v[16:17], v[16:17], 0, s[44:45]
	global_load_dwordx4 v[84:87], v[16:17], off nt
	v_lshl_add_u64 v[16:17], v[16:17], 0, s[44:45]
	global_load_dwordx4 v[80:83], v[16:17], off nt
	v_lshl_add_u64 v[16:17], v[16:17], 0, s[44:45]
	global_load_dwordx4 v[76:79], v[16:17], off nt
.LBB0_807:
	s_cmp_eq_u32 s8, 3
	s_cselect_b64 s[30:31], -1, 0
	s_cmp_lg_u32 s8, 3
	s_cbranch_scc1 .LBB0_810
	s_or_b32 s6, s6, 2
	s_lshl_b32 s10, s6, 7
	s_ashr_i32 s11, s10, 31
	s_lshl_b64 s[10:11], s[10:11], 2
	s_add_u32 s10, s66, s10
	s_addc_u32 s11, s67, s11
	s_ashr_i32 s7, s6, 31
	s_lshl_b64 s[6:7], s[6:7], 16
	s_add_u32 s6, s62, s6
	v_lshl_add_u64 v[16:17], v[114:115], 2, s[10:11]
	v_mov_b32_e32 v9, v11
	s_addc_u32 s7, s63, s7
	v_lshl_add_u64 v[16:17], v[16:17], 0, v[8:9]
	v_lshl_add_u64 v[28:29], v[116:117], 2, s[6:7]
	global_load_dwordx4 v[16:19], v[16:17], off nt
	global_load_dwordx4 v[20:23], v[28:29], off nt
	v_lshl_add_u64 v[32:33], v[28:29], 0, s[44:45]
	global_load_dwordx4 v[28:31], v[32:33], off nt
	v_lshl_add_u64 v[36:37], v[32:33], 0, s[44:45]
	global_load_dwordx4 v[32:35], v[36:37], off nt
	v_lshl_add_u64 v[36:37], v[36:37], 0, s[44:45]
	global_load_dwordx4 v[40:43], v[36:37], off nt
	v_lshl_add_u64 v[36:37], v[36:37], 0, s[44:45]
	global_load_dwordx4 v[56:59], v[36:37], off nt
	v_lshl_add_u64 v[36:37], v[36:37], 0, s[44:45]
	global_load_dwordx4 v[64:67], v[36:37], off nt
	v_lshl_add_u64 v[36:37], v[36:37], 0, s[44:45]
	global_load_dwordx4 v[68:71], v[36:37], off nt
	v_lshl_add_u64 v[36:37], v[36:37], 0, s[44:45]
	global_load_dwordx4 v[72:75], v[36:37], off nt
	s_andn2_b64 vcc, exec, s[4:5]
	s_cbranch_vccz .LBB0_811

; __device__ __forceinline__ void hgrn_pass2(const RecurBufs& rb, const float* hgn_l, float* state_out_l, int u, int tid, LAS unsigned char* lds) {
;     ...
;     const int e0 = 64 * eh + 4 * c;
;     const f32x4 hn = *(const f32x4*)(hgn_l + e0);
;     const float* cvb = rb.cv + ((size_t)((b * 8 + h) * 32 + seg * NCH) * 3) * 128;
;     const int sr = tid >> 4, sc16 = tid & 15;
;     const size_t rowS = (size_t)b * SEQ + seg * SEGLEN;
;     v4u pre[6];
;     {   const bf16* gq = rb.proj + (rowS + sr) * LDP + PC_Q + h * 128 + sc16 * 8;
;         pre[0] = *(const v4u*)gq; pre[1] = *(const v4u*)(gq + 32 * (size_t)LDP); pre[2] = *(const v4u*)(gq + PC_F); pre[3] = *(const v4u*)(gq + 32 * (size_t)LDP + PC_F);
;         pre[4] = *(const v4u*)(gq + PC_I); pre[5] = *(const v4u*)(gq + 32 * (size_t)LDP + PC_I); }
;     float cvn = tid < 384 ? cvb[tid] : 0.f; f32x4 ern = *(const f32x4*)(cvb + 16 * w + 4 * g);
.LBB0_815:
	s_waitcnt vmcnt(0) lgkmcnt(0)
	v_and_b32_e32 v72, 15, v112
	v_ashrrev_i32_e32 v73, 8, v112
	s_ashr_i32 s36, s69, 5
	v_lshlrev_b32_e32 v74, 6, v73
	v_lshlrev_b32_e32 v134, 2, v72
	s_bfe_u32 s3, s69, 0x30002
	v_or_b32_e32 v64, v74, v134
	v_readlane_b32 s4, v255, 53
	s_lshl_b32 s2, s36, 3
	v_ashrrev_i32_e32 v65, 31, v64
	v_readlane_b32 s5, v255, 54
	s_or_b32 s2, s2, s3
	v_ashrrev_i32_e32 v66, 4, v112
	v_lshl_add_u64 v[16:17], v[64:65], 2, s[4:5]
	s_lshl_b32 s4, s2, 5
	s_lshl_b32 s5, s8, 3
	s_or_b32 s4, s4, s5
	s_mul_hi_i32 s5, s4, 0x600
	s_mulk_i32 s4, 0x600
	s_add_u32 s6, s60, s4
	s_addc_u32 s7, s61, s5
	s_ashr_i32 s37, s36, 31
	s_lshl_b64 s[58:59], s[36:37], 11
	s_lshl_b32 s4, s8, 9
	s_or_b32 s4, s58, s4
	s_mov_b32 s5, s59
	v_ashrrev_i32_e32 v67, 31, v66
	v_lshl_add_u64 v[20:21], s[4:5], 0, v[66:67]
	v_mov_b64_e32 v[22:23], s[28:29]
	v_mad_u64_u32 v[22:23], s[4:5], v20, s77, v[22:23]
	v_mad_i32_i24 v23, v21, s77, v23
	s_lshl_b32 s64, s3, 8
	v_lshl_add_u64 v[20:21], v[22:23], 0, s[64:65]
	v_lshlrev_b32_e32 v10, 4, v72
	v_lshl_add_u64 v[48:49], v[20:21], 0, v[10:11]
	v_add_co_u32_e32 v40, vcc, 0xc4000, v48
	global_load_dwordx4 v[16:19], v[16:17], off nt
	s_nop 0
	v_addc_co_u32_e32 v41, vcc, 0, v49, vcc
	v_add_co_u32_e32 v50, vcc, 0x1000, v48
	global_load_dwordx4 v[20:23], v[48:49], off nt
	global_load_dwordx4 v[28:31], v[48:49], off offset:2048 nt
	global_load_dwordx4 v[32:35], v[40:41], off nt
	s_nop 0
	global_load_dwordx4 v[40:43], v[40:41], off offset:2048 nt
	v_addc_co_u32_e32 v51, vcc, 0, v49, vcc
	v_add_co_u32_e32 v56, vcc, 0xc5000, v48
	s_movk_i32 s4, 0x180
	s_nop 0
	v_addc_co_u32_e32 v57, vcc, 0, v49, vcc
	global_load_dwordx4 v[48:51], v[50:51], off nt
	s_nop 0
	global_load_dwordx4 v[56:59], v[56:57], off nt
	s_movk_i32 s8, 0x17f
	v_cmp_gt_i32_e64 s[4:5], s4, v112
	v_cmp_lt_i32_e32 vcc, s8, v112
	s_and_saveexec_b64 s[8:9], vcc
	s_xor_b64 s[8:9], exec, s[8:9]
	v_mov_b32_e32 v113, v11
	s_or_saveexec_b64 s[8:9], s[8:9]
	v_mov_b32_e32 v135, 0
	s_xor_b64 exec, exec, s[8:9]
	s_cbranch_execz .LBB0_819
	v_ashrrev_i32_e32 v113, 31, v112
	v_lshl_add_u64 v[68:69], v[112:113], 2, s[6:7]
	global_load_dword v135, v[68:69], off
.LBB0_819:
	s_or_b64 exec, exec, s[8:9]
	v_lshlrev_b64 v[78:79], 2, v[114:115]
	v_lshl_add_u64 v[68:69], s[6:7], 0, v[78:79]
	v_mov_b32_e32 v9, v11
	v_lshl_add_u64 v[8:9], v[68:69], 0, v[8:9]
	global_load_dwordx4 v[68:71], v[8:9], off nt
	v_and_b32_e32 v67, 3, v123
	v_readlane_b32 s6, v255, 17
	v_and_b32_e32 v85, 12, v116
	v_lshlrev_b32_e32 v80, 4, v67
	v_lshl_add_u32 v9, v112, 2, s6
	v_or_b32_e32 v86, v85, v74
	v_or_b32_e32 v87, v74, v72
	v_lshlrev_b32_e32 v74, 2, v114
	v_readlane_b32 s6, v255, 18
	s_movk_i32 s73, 0x110
	v_or_b32_e32 v81, v80, v72
	v_add_u32_e32 v88, s6, v74
	v_readlane_b32 s6, v255, 19
	s_and_b32 s8, s68, 3
	v_mad_u32_u24 v84, v81, s73, 0
	v_bfe_u32 v81, v112, 2, 2
	v_add3_u32 v138, s6, v74, v134
	v_lshrrev_b32_e32 v74, 1, v112
	s_lshl_b32 s51, s8, 3
	s_mul_i32 s70, s8, 0xc40000
	s_lshl_b32 s71, s8, 20
	s_lshl_b32 s72, s8, 9
	v_and_or_b32 v74, v74, 24, v81
	v_cmp_eq_u32_e64 s[8:9], 0, v67
	v_cmp_ne_u32_e64 s[10:11], 0, v67
	v_cmp_eq_u32_e64 s[20:21], 1, v67
	v_cmp_lt_u32_e64 s[22:23], 1, v67
	v_cmp_eq_u32_e64 s[24:25], 2, v67
	v_cmp_eq_u32_e64 s[26:27], 3, v67
	v_bfe_u32 v67, v112, 2, 4
	s_lshl_b32 s50, s3, 5
	v_mul_lo_u32 v8, v66, s73
	v_mad_u32_u24 v91, v74, s73, 0
	v_mad_u32_u24 v92, v67, s73, 0
	v_mul_lo_u32 v87, v87, s73
	s_lshl_b32 s73, s36, 8
	s_or_b32 s50, s73, s50
	s_or_b32 s50, s50, s51
	s_mul_hi_i32 s51, s50, 0x600
	s_mulk_i32 s50, 0x600
	s_add_u32 s50, s50, 0x4d200600
	s_addc_u32 s51, s51, 0
	v_and_b32_e32 v83, 48, v112
	v_lshl_add_u64 v[112:113], v[112:113], 2, s[50:51]
	v_mov_b32_e32 v81, s51
	s_mul_i32 s51, s36, 0x3100000
	v_mul_u32_u24_e32 v90, 0x110, v74
	v_or_b32_e32 v74, v80, v122
	v_or_b32_e32 v80, s50, v83
	s_mul_hi_i32 s50, s36, 0x3100000
	s_add_u32 s70, s51, s70
	s_addc_u32 s51, s50, 0
	s_or_b32 s50, s70, s64
	v_add_u32_e32 v82, 0, v8
	v_or_b32_e32 v8, v122, v114
	v_or_b32_e32 v89, v85, v114
	v_lshl_add_u64 v[114:115], v[80:81], 0, v[78:79]
	v_mov_b64_e32 v[78:79], s[50:51]
	s_lshl_b64 s[36:37], s[36:37], 22
	v_mad_i64_i32 v[116:117], s[50:51], v66, s77, v[78:79]
	v_mad_u64_u32 v[66:67], s[50:51], v74, s77, v[78:79]
	v_lshlrev_b64 v[64:65], 1, v[64:65]
	s_or_b32 s36, s36, s71
	v_lshlrev_b32_e32 v75, 1, v8
	v_mul_u32_u24_e32 v140, 0x110, v72
	v_lshl_add_u64 v[118:119], v[66:67], 0, v[64:65]
	v_lshl_or_b32 v66, v74, 11, s36
	s_add_u32 s36, s58, s72
	v_lshl_add_u32 v139, v73, 2, s87
	v_add3_u32 v141, 0, v75, v140
	v_or_b32_e32 v73, 2, v122
	v_mov_b32_e32 v75, v11
	v_or_b32_e32 v66, s64, v66
	v_mov_b32_e32 v67, s37
	s_addc_u32 s37, s59, 0
	v_cmp_gt_u32_e64 s[16:17], v73, v72
	v_or_b32_e32 v73, 3, v122
	v_lshl_add_u64 v[120:121], v[66:67], 0, v[64:65]
	v_lshl_add_u64 v[66:67], s[36:37], 0, v[74:75]
	v_cmp_eq_u32_e64 s[6:7], 0, v72
	v_cmp_gt_u32_e64 s[12:13], v122, v72
	v_cmp_lt_u32_e64 s[14:15], v122, v72
	v_cmp_gt_u32_e64 s[18:19], v73, v72
	v_lshl_or_b32 v116, v72, 4, v116
	v_lshlrev_b64 v[72:73], 11, v[66:67]
	v_or_b32_e32 v72, s64, v72
	v_mov_b32_e32 v76, s64
	v_mov_b32_e32 v77, v11
	v_lshl_add_u64 v[72:73], v[72:73], 0, v[64:65]
	s_mov_b64 s[36:37], 0x30500000
	v_lshl_add_u64 v[122:123], v[72:73], 0, s[36:37]
	v_mad_u64_u32 v[72:73], s[36:37], v66, s77, v[76:77]
	v_mad_i32_i24 v73, v67, s77, v73
	v_add_u32_e32 v136, 0, v83
	v_lshl_add_u32 v89, v89, 1, 0
	v_lshlrev_b32_e32 v85, 1, v85
	v_lshlrev_b32_e32 v86, 1, v86
	v_lshlrev_b32_e32 v143, 3, v74
	v_lshl_add_u64 v[64:65], v[72:73], 0, v[64:65]
	s_mov_b64 s[36:37], 0x17601800
	s_mov_b32 s3, 8
	v_add_u32_e32 v142, 0xcc00, v141
	v_or_b32_e32 v144, 8, v143
	v_or_b32_e32 v145, 16, v143
	v_or_b32_e32 v146, 24, v143
	v_lshl_add_u64 v[124:125], v[64:65], 0, s[36:37]
	v_add_u32_e32 v10, v82, v10
	v_add_u32_e32 v147, v84, v83
	v_add_u32_e32 v149, v136, v87
	v_add_u32_e32 v156, v88, v83
	v_add_u32_e32 v157, v89, v90
	v_add_u32_e32 v158, v91, v85
	v_add_u32_e32 v159, v92, v86
	s_branch .LBB0_821

; #define LAS __attribute__((address_space(3)))
; __device__ __forceinline__ void hgrn_pass2(const RecurBufs& rb, const float* hgn_l, float* state_out_l, int u, int tid, LAS unsigned char* lds) {
;     ...
;     for (int ch = 0; ch < NCH; ++ch) {
;         const size_t row0 = rowS + ch * RC;
;         *(LAS v4u*)(Qt + sr * PQ + sc16 * 16) = pre[0]; *(LAS v4u*)(Qt + (sr + 32) * PQ + sc16 * 16) = pre[1];
;         *(LAS v4u*)(Kt + sr * PQ + sc16 * 16) = pre[2]; *(LAS v4u*)(Kt + (sr + 32) * PQ + sc16 * 16) = pre[3];
;         *(LAS v4u*)(V + sr * PQ + sc16 * 16) = pre[4]; *(LAS v4u*)(V + (sr + 32) * PQ + sc16 * 16) = pre[5];
;         if (ch + 1 < NCH) { const bf16* gq = rb.proj + (row0 + RC + sr) * LDP + PC_Q + h * 128 + sc16 * 8;
;             pre[0] = *(const v4u*)gq; pre[1] = *(const v4u*)(gq + 32 * (size_t)LDP); pre[2] = *(const v4u*)(gq + PC_F); pre[3] = *(const v4u*)(gq + 32 * (size_t)LDP + PC_F);
;             pre[4] = *(const v4u*)(gq + PC_I); pre[5] = *(const v4u*)(gq + 32 * (size_t)LDP + PC_I); }
.LBB0_821:
	s_cmp_lg_u32 s3, 1
	s_cselect_b64 s[36:37], -1, 0
	s_cmp_eq_u32 s3, 1
	s_waitcnt vmcnt(0) lgkmcnt(0)
	ds_write_b128 v10, v[20:23]
	ds_write_b128 v10, v[32:35] offset:8704
	ds_write_b128 v10, v[28:31] offset:17408
	ds_write_b128 v10, v[40:43] offset:26112
	ds_write_b128 v10, v[48:51] offset:34816
	ds_write_b128 v10, v[56:59] offset:43520
	s_cbranch_scc1 .LBB0_827
	v_lshl_add_u64 v[48:49], s[34:35], 0, v[116:117]
	v_add_co_u32_e32 v28, vcc, 0x17788000, v48
	s_nop 1
	v_addc_co_u32_e32 v29, vcc, 0, v49, vcc
	v_add_co_u32_e32 v40, vcc, 0x1784c000, v48
	s_nop 1
	v_addc_co_u32_e32 v41, vcc, 0, v49, vcc
	v_add_co_u32_e32 v50, vcc, 0x17789000, v48
	global_load_dwordx4 v[20:23], v[28:29], off nt
	s_nop 0
	global_load_dwordx4 v[28:31], v[28:29], off offset:2048 nt
	s_nop 0
	global_load_dwordx4 v[32:35], v[40:41], off nt
	s_nop 0
	global_load_dwordx4 v[40:43], v[40:41], off offset:2048 nt
	v_addc_co_u32_e32 v51, vcc, 0, v49, vcc
	v_add_co_u32_e32 v56, vcc, 0x1784d000, v48
	s_nop 1
	v_addc_co_u32_e32 v57, vcc, 0, v49, vcc
	global_load_dwordx4 v[48:51], v[50:51], off nt
	s_nop 0
	global_load_dwordx4 v[56:59], v[56:57], off nt
	s_and_saveexec_b64 s[50:51], s[4:5]
	s_cbranch_execnz .LBB0_828

; __device__ __forceinline__ void hgrn_pass2(const RecurBufs& rb, const float* hgn_l, float* state_out_l, int u, int tid, LAS unsigned char* lds) {
;     ...
;         if (tid < 384) vec[tid] = cvn;
;         {
;             const f32x4 er = ern;
;             if (ch + 1 < NCH) { if (tid < 384) cvn = cvb[(size_t)(ch + 1) * 384 + tid]; ern = *(const f32x4*)(cvb + (size_t)(ch + 1) * 384 + 16 * w + 4 * g); }
.LBB0_826:
	s_or_b64 exec, exec, s[36:37]
	v_lshl_add_u64 v[64:65], s[34:35], 0, v[114:115]
	global_load_dwordx4 v[64:67], v[64:65], off nt
	s_branch .LBB0_830

; #define LAUNDER_PTR(p) do {} while (0)
; #define LAUNDER_PTR(p) asm volatile("" : "+v"(p))
; __device__ __forceinline__ void ssd_pass2(const RecurBufs& rb, const float* d_skip, const float* ssm_norm, float* state_out_l, int u, int tid, LAS unsigned char* lds) {
;     ...
;     for (int s = 0; s < seg; s += 2) {
;         f32x4 L0[4][4], L1[4][4]; const bool two = s + 1 < seg;
;         const int ua = u - seg + s, ub = two ? ua + 1 : ua;
;         const float dca = __expf(rb.tseg[ua * 4 + k]), dcb = __expf(rb.tseg[ub * 4 + k]);
;         {   const float* hp = rb.hseg + (size_t)ua * 32768 + tid * 4;
; #pragma unroll
;             for (int nt = 0; nt < 4; ++nt)
; #pragma unroll
;                 for (int pt = 0; pt < 4; ++pt) { LAUNDER_PTR(hp); L0[nt][pt] = *(const f32x4*)hp; hp += 2048; } }
;         if (two) { const float* hp = rb.hseg + (size_t)ub * 32768 + tid * 4;
; #pragma unroll
;             for (int nt = 0; nt < 4; ++nt)
; #pragma unroll
;                 for (int pt = 0; pt < 4; ++pt) { LAUNDER_PTR(hp); L1[nt][pt] = *(const f32x4*)hp; hp += 2048; } }
; #pragma unroll
;         for (int nt = 0; nt < 4; ++nt)
; #pragma unroll
;             for (int pt = 0; pt < 4; ++pt) { H[nt][pt] = H[nt][pt] * dca + L0[nt][pt]; if (two) H[nt][pt] = H[nt][pt] * dcb + L1[nt][pt]; } }
.LBB0_850:
	s_and_b32 s1, s0, 3
	v_mov_b32_e32 v138, v137
	s_xor_b32 s6, s1, 3
	s_cmp_eq_u32 s1, 3
	v_ashrrev_i32_e32 v189, 7, v138
	v_lshlrev_b32_e32 v134, 2, v138
	s_cbranch_scc1 .LBB0_855
	s_and_b32 s2, s0, -4
	s_cmp_gt_u32 s6, 1
	s_cselect_b64 vcc, -1, 0
	v_cndmask_b32_e64 v0, 0, 1, vcc
	v_ashrrev_i32_e32 v135, 31, v134
	v_or_b32_e32 v16, s2, v0
	s_ashr_i32 s3, s2, 31
	v_lshl_add_u32 v0, s2, 2, v189
	v_lshl_add_u64 v[8:9], v[134:135], 2, s[26:27]
	s_lshl_b64 s[4:5], s[2:3], 17
	v_ashrrev_i32_e32 v1, 31, v0
	v_lshl_add_u32 v2, v16, 2, v189
	v_lshl_add_u64 v[0:1], v[0:1], 2, s[30:31]
	v_ashrrev_i32_e32 v3, 31, v2
	v_lshl_add_u64 v[4:5], v[8:9], 0, s[4:5]
	v_lshl_add_u64 v[2:3], v[2:3], 2, s[30:31]
	global_load_dword v135, v[0:1], off
	global_load_dword v10, v[2:3], off
	global_load_dwordx4 v[0:3], v[4:5], off nt
	v_lshl_add_u64 v[12:13], v[4:5], 0, s[44:45]
	global_load_dwordx4 v[4:7], v[12:13], off nt
	v_lshl_add_u64 v[18:19], v[12:13], 0, s[44:45]
	global_load_dwordx4 v[12:15], v[18:19], off nt
	v_lshl_add_u64 v[22:23], v[18:19], 0, s[44:45]
	global_load_dwordx4 v[18:21], v[22:23], off nt
	v_lshl_add_u64 v[26:27], v[22:23], 0, s[44:45]
	global_load_dwordx4 v[22:25], v[26:27], off nt
	v_lshl_add_u64 v[30:31], v[26:27], 0, s[44:45]
	global_load_dwordx4 v[26:29], v[30:31], off nt
	v_lshl_add_u64 v[34:35], v[30:31], 0, s[44:45]
	global_load_dwordx4 v[30:33], v[34:35], off nt
	v_lshl_add_u64 v[38:39], v[34:35], 0, s[44:45]
	global_load_dwordx4 v[34:37], v[38:39], off nt
	v_lshl_add_u64 v[42:43], v[38:39], 0, s[44:45]
	global_load_dwordx4 v[38:41], v[42:43], off nt
	v_lshl_add_u64 v[46:47], v[42:43], 0, s[44:45]
	global_load_dwordx4 v[42:45], v[46:47], off nt
	v_lshl_add_u64 v[50:51], v[46:47], 0, s[44:45]
	global_load_dwordx4 v[46:49], v[50:51], off nt
	v_lshl_add_u64 v[54:55], v[50:51], 0, s[44:45]
	global_load_dwordx4 v[50:53], v[54:55], off nt
	v_lshl_add_u64 v[58:59], v[54:55], 0, s[44:45]
	global_load_dwordx4 v[54:57], v[58:59], off nt
	v_lshl_add_u64 v[62:63], v[58:59], 0, s[44:45]
	global_load_dwordx4 v[58:61], v[62:63], off nt
	v_lshl_add_u64 v[66:67], v[62:63], 0, s[44:45]
	global_load_dwordx4 v[62:65], v[66:67], off nt
	v_lshl_add_u64 v[66:67], v[66:67], 0, s[44:45]
	global_load_dwordx4 v[66:69], v[66:67], off nt
	s_cmp_lt_u32 s6, 2
	s_cbranch_scc1 .LBB0_853
	v_ashrrev_i32_e32 v17, 31, v16
	v_lshlrev_b64 v[16:17], 17, v[16:17]
	v_lshl_add_u64 v[16:17], v[8:9], 0, v[16:17]
	global_load_dwordx4 v[130:133], v[16:17], off nt
	v_lshl_add_u64 v[16:17], v[16:17], 0, s[44:45]
	global_load_dwordx4 v[126:129], v[16:17], off nt
	v_lshl_add_u64 v[16:17], v[16:17], 0, s[44:45]
	global_load_dwordx4 v[122:125], v[16:17], off nt
	v_lshl_add_u64 v[16:17], v[16:17], 0, s[44:45]
	global_load_dwordx4 v[118:121], v[16:17], off nt
	v_lshl_add_u64 v[16:17], v[16:17], 0, s[44:45]
	global_load_dwordx4 v[114:117], v[16:17], off nt
	v_lshl_add_u64 v[16:17], v[16:17], 0, s[44:45]
	global_load_dwordx4 v[110:113], v[16:17], off nt
	v_lshl_add_u64 v[16:17], v[16:17], 0, s[44:45]
	global_load_dwordx4 v[106:109], v[16:17], off nt
	v_lshl_add_u64 v[16:17], v[16:17], 0, s[44:45]
	global_load_dwordx4 v[102:105], v[16:17], off nt
	v_lshl_add_u64 v[16:17], v[16:17], 0, s[44:45]
	global_load_dwordx4 v[98:101], v[16:17], off nt
	v_lshl_add_u64 v[16:17], v[16:17], 0, s[44:45]
	global_load_dwordx4 v[94:97], v[16:17], off nt
	v_lshl_add_u64 v[16:17], v[16:17], 0, s[44:45]
	global_load_dwordx4 v[90:93], v[16:17], off nt
	v_lshl_add_u64 v[16:17], v[16:17], 0, s[44:45]
	global_load_dwordx4 v[86:89], v[16:17], off nt
	v_lshl_add_u64 v[16:17], v[16:17], 0, s[44:45]
	global_load_dwordx4 v[82:85], v[16:17], off nt
	v_lshl_add_u64 v[16:17], v[16:17], 0, s[44:45]
	global_load_dwordx4 v[78:81], v[16:17], off nt
	v_lshl_add_u64 v[16:17], v[16:17], 0, s[44:45]
	global_load_dwordx4 v[74:77], v[16:17], off nt
	v_lshl_add_u64 v[16:17], v[16:17], 0, s[44:45]
	global_load_dwordx4 v[70:73], v[16:17], off nt
.LBB0_853:
	s_waitcnt vmcnt(0) lgkmcnt(0)
	v_mul_f32_e32 v16, 0x3fb8aa3b, v135
	v_exp_f32_e32 v16, v16
	v_mul_f32_e32 v10, 0x3fb8aa3b, v10
	v_exp_f32_e32 v10, v10
	s_cmp_eq_u32 s1, 0
	v_mul_f32_e32 v136, 0, v16
	v_pk_add_f32 v[0:1], v[0:1], v[136:137] op_sel_hi:[1,0]
	v_pk_add_f32 v[4:5], v[136:137], v[4:5] op_sel_hi:[0,1]
	v_pk_fma_f32 v[16:17], v[10:11], v[0:1], v[130:131] op_sel_hi:[0,1,1]
	v_cndmask_b32_e32 v1, v1, v17, vcc
	v_cndmask_b32_e32 v0, v0, v16, vcc
	v_pk_fma_f32 v[16:17], v[10:11], v[4:5], v[126:127] op_sel_hi:[0,1,1]
	v_pk_add_f32 v[14:15], v[136:137], v[14:15] op_sel_hi:[0,1]
	v_pk_add_f32 v[12:13], v[136:137], v[12:13] op_sel_hi:[0,1]
	v_cndmask_b32_e32 v5, v5, v17, vcc
	v_cndmask_b32_e32 v4, v4, v16, vcc
	v_pk_fma_f32 v[122:123], v[10:11], v[12:13], v[122:123] op_sel_hi:[0,1,1]
	v_pk_fma_f32 v[16:17], v[10:11], v[14:15], v[124:125] op_sel_hi:[0,1,1]
	v_cndmask_b32_e32 v17, v15, v17, vcc
	v_cndmask_b32_e32 v16, v14, v16, vcc
	v_cndmask_b32_e32 v15, v13, v123, vcc
	v_cndmask_b32_e32 v14, v12, v122, vcc
	v_pk_add_f32 v[12:13], v[136:137], v[20:21] op_sel_hi:[0,1]
	v_pk_fma_f32 v[20:21], v[10:11], v[12:13], v[120:121] op_sel_hi:[0,1,1]
	v_cndmask_b32_e32 v21, v13, v21, vcc
	v_cndmask_b32_e32 v20, v12, v20, vcc
	v_pk_add_f32 v[12:13], v[136:137], v[24:25] op_sel_hi:[0,1]
	v_pk_fma_f32 v[24:25], v[10:11], v[12:13], v[116:117] op_sel_hi:[0,1,1]
	v_cndmask_b32_e32 v25, v13, v25, vcc
	v_cndmask_b32_e32 v24, v12, v24, vcc
	v_pk_add_f32 v[12:13], v[136:137], v[28:29] op_sel_hi:[0,1]
	v_pk_fma_f32 v[28:29], v[10:11], v[12:13], v[112:113] op_sel_hi:[0,1,1]
	v_cndmask_b32_e32 v29, v13, v29, vcc
	v_cndmask_b32_e32 v28, v12, v28, vcc
	v_pk_add_f32 v[12:13], v[136:137], v[32:33] op_sel_hi:[0,1]
; __device__ __forceinline__ void ssd_pass2(const RecurBufs& rb, const float* d_skip, const float* ssm_norm, float* state_out_l, int u, int tid, LAS unsigned char* lds) {
;     ...
; #pragma unroll
;         for (int nt = 0; nt < 4; ++nt)
; #pragma unroll
;             for (int pt = 0; pt < 4; ++pt) { H[nt][pt] = H[nt][pt] * dca + L0[nt][pt]; if (two) H[nt][pt] = H[nt][pt] * dcb + L1[nt][pt]; } }
	v_pk_fma_f32 v[32:33], v[10:11], v[12:13], v[108:109] op_sel_hi:[0,1,1]
	v_cndmask_b32_e32 v33, v13, v33, vcc
	v_cndmask_b32_e32 v32, v12, v32, vcc
	v_pk_add_f32 v[12:13], v[136:137], v[36:37] op_sel_hi:[0,1]
	v_pk_fma_f32 v[36:37], v[10:11], v[12:13], v[104:105] op_sel_hi:[0,1,1]
	v_cndmask_b32_e32 v37, v13, v37, vcc
	v_cndmask_b32_e32 v36, v12, v36, vcc
	v_pk_add_f32 v[12:13], v[136:137], v[40:41] op_sel_hi:[0,1]
	v_pk_fma_f32 v[40:41], v[10:11], v[12:13], v[100:101] op_sel_hi:[0,1,1]
	v_cndmask_b32_e32 v41, v13, v41, vcc
	v_cndmask_b32_e32 v40, v12, v40, vcc
	v_pk_add_f32 v[12:13], v[136:137], v[44:45] op_sel_hi:[0,1]
	v_pk_fma_f32 v[44:45], v[10:11], v[12:13], v[96:97] op_sel_hi:[0,1,1]
	v_cndmask_b32_e32 v45, v13, v45, vcc
	v_cndmask_b32_e32 v44, v12, v44, vcc
	v_pk_add_f32 v[12:13], v[136:137], v[48:49] op_sel_hi:[0,1]
	v_pk_fma_f32 v[48:49], v[10:11], v[12:13], v[92:93] op_sel_hi:[0,1,1]
	v_cndmask_b32_e32 v49, v13, v49, vcc
	v_cndmask_b32_e32 v48, v12, v48, vcc
	v_pk_add_f32 v[12:13], v[136:137], v[52:53] op_sel_hi:[0,1]
	v_pk_fma_f32 v[52:53], v[10:11], v[12:13], v[88:89] op_sel_hi:[0,1,1]
	v_cndmask_b32_e32 v53, v13, v53, vcc
	v_cndmask_b32_e32 v52, v12, v52, vcc
	v_pk_add_f32 v[12:13], v[136:137], v[56:57] op_sel_hi:[0,1]
	v_pk_fma_f32 v[56:57], v[10:11], v[12:13], v[84:85] op_sel_hi:[0,1,1]
	v_cndmask_b32_e32 v57, v13, v57, vcc
	v_cndmask_b32_e32 v56, v12, v56, vcc
	v_pk_add_f32 v[12:13], v[136:137], v[60:61] op_sel_hi:[0,1]
	v_pk_fma_f32 v[60:61], v[10:11], v[12:13], v[80:81] op_sel_hi:[0,1,1]
	v_cndmask_b32_e32 v61, v13, v61, vcc
	v_cndmask_b32_e32 v60, v12, v60, vcc
	v_pk_add_f32 v[12:13], v[136:137], v[64:65] op_sel_hi:[0,1]
	v_pk_fma_f32 v[64:65], v[10:11], v[12:13], v[76:77] op_sel_hi:[0,1,1]
	v_pk_add_f32 v[2:3], v[2:3], v[136:137] op_sel_hi:[1,0]
	v_pk_add_f32 v[6:7], v[136:137], v[6:7] op_sel_hi:[0,1]
	v_pk_add_f32 v[18:19], v[136:137], v[18:19] op_sel_hi:[0,1]
	v_pk_add_f32 v[22:23], v[136:137], v[22:23] op_sel_hi:[0,1]
	v_pk_add_f32 v[26:27], v[136:137], v[26:27] op_sel_hi:[0,1]
	v_pk_add_f32 v[30:31], v[136:137], v[30:31] op_sel_hi:[0,1]
	v_pk_add_f32 v[34:35], v[136:137], v[34:35] op_sel_hi:[0,1]
	v_pk_add_f32 v[38:39], v[136:137], v[38:39] op_sel_hi:[0,1]
	v_pk_add_f32 v[42:43], v[136:137], v[42:43] op_sel_hi:[0,1]
	v_pk_add_f32 v[46:47], v[136:137], v[46:47] op_sel_hi:[0,1]
	v_pk_add_f32 v[50:51], v[136:137], v[50:51] op_sel_hi:[0,1]
	v_pk_add_f32 v[54:55], v[136:137], v[54:55] op_sel_hi:[0,1]
	v_pk_add_f32 v[58:59], v[136:137], v[58:59] op_sel_hi:[0,1]
	v_pk_add_f32 v[62:63], v[136:137], v[62:63] op_sel_hi:[0,1]
	v_cndmask_b32_e32 v65, v13, v65, vcc
	v_cndmask_b32_e32 v64, v12, v64, vcc
	v_pk_add_f32 v[12:13], v[136:137], v[68:69] op_sel_hi:[0,1]
	v_pk_add_f32 v[66:67], v[136:137], v[66:67] op_sel_hi:[0,1]
	v_pk_fma_f32 v[130:131], v[10:11], v[2:3], v[132:133] op_sel_hi:[0,1,1]
	v_pk_fma_f32 v[126:127], v[10:11], v[6:7], v[128:129] op_sel_hi:[0,1,1]
	v_pk_fma_f32 v[118:119], v[10:11], v[18:19], v[118:119] op_sel_hi:[0,1,1]
	v_pk_fma_f32 v[114:115], v[10:11], v[22:23], v[114:115] op_sel_hi:[0,1,1]
	v_pk_fma_f32 v[110:111], v[10:11], v[26:27], v[110:111] op_sel_hi:[0,1,1]
	v_pk_fma_f32 v[106:107], v[10:11], v[30:31], v[106:107] op_sel_hi:[0,1,1]
	v_pk_fma_f32 v[102:103], v[10:11], v[34:35], v[102:103] op_sel_hi:[0,1,1]
	v_pk_fma_f32 v[98:99], v[10:11], v[38:39], v[98:99] op_sel_hi:[0,1,1]
	v_pk_fma_f32 v[94:95], v[10:11], v[42:43], v[94:95] op_sel_hi:[0,1,1]
	v_pk_fma_f32 v[90:91], v[10:11], v[46:47], v[90:91] op_sel_hi:[0,1,1]
	v_pk_fma_f32 v[86:87], v[10:11], v[50:51], v[86:87] op_sel_hi:[0,1,1]
	v_pk_fma_f32 v[82:83], v[10:11], v[54:55], v[82:83] op_sel_hi:[0,1,1]
	v_pk_fma_f32 v[78:79], v[10:11], v[58:59], v[78:79] op_sel_hi:[0,1,1]
	v_pk_fma_f32 v[74:75], v[10:11], v[62:63], v[74:75] op_sel_hi:[0,1,1]
	v_pk_fma_f32 v[70:71], v[10:11], v[66:67], v[70:71] op_sel_hi:[0,1,1]
	v_pk_fma_f32 v[68:69], v[10:11], v[12:13], v[72:73] op_sel_hi:[0,1,1]
	v_cndmask_b32_e32 v3, v3, v131, vcc
	v_cndmask_b32_e32 v2, v2, v130, vcc
	v_cndmask_b32_e32 v7, v7, v127, vcc
	v_cndmask_b32_e32 v6, v6, v126, vcc
	v_cndmask_b32_e32 v19, v19, v119, vcc
	v_cndmask_b32_e32 v18, v18, v118, vcc
	v_cndmask_b32_e32 v23, v23, v115, vcc
	v_cndmask_b32_e32 v22, v22, v114, vcc
	v_cndmask_b32_e32 v27, v27, v111, vcc
	v_cndmask_b32_e32 v26, v26, v110, vcc
	v_cndmask_b32_e32 v31, v31, v107, vcc
	v_cndmask_b32_e32 v30, v30, v106, vcc
	v_cndmask_b32_e32 v35, v35, v103, vcc
	v_cndmask_b32_e32 v34, v34, v102, vcc
	v_cndmask_b32_e32 v39, v39, v99, vcc
	v_cndmask_b32_e32 v38, v38, v98, vcc
	v_cndmask_b32_e32 v43, v43, v95, vcc
	v_cndmask_b32_e32 v42, v42, v94, vcc
	v_cndmask_b32_e32 v47, v47, v91, vcc
	v_cndmask_b32_e32 v46, v46, v90, vcc
	v_cndmask_b32_e32 v51, v51, v87, vcc
	v_cndmask_b32_e32 v50, v50, v86, vcc
	v_cndmask_b32_e32 v55, v55, v83, vcc
	v_cndmask_b32_e32 v54, v54, v82, vcc
	v_cndmask_b32_e32 v59, v59, v79, vcc
	v_cndmask_b32_e32 v58, v58, v78, vcc
	v_cndmask_b32_e32 v63, v63, v75, vcc
	v_cndmask_b32_e32 v62, v62, v74, vcc
	v_cndmask_b32_e32 v69, v13, v69, vcc
	v_cndmask_b32_e32 v68, v12, v68, vcc
	v_cndmask_b32_e32 v67, v67, v71, vcc
	v_cndmask_b32_e32 v66, v66, v70, vcc
	s_cbranch_scc0 .LBB0_856
; #define LAUNDER_PTR(p) do {} while (0)
; #define LAUNDER_PTR(p) asm volatile("" : "+v"(p))
; __device__ __forceinline__ void ssd_pass2(const RecurBufs& rb, const float* d_skip, const float* ssm_norm, float* state_out_l, int u, int tid, LAS unsigned char* lds) {
;     ...
;     for (int s = 0; s < seg; s += 2) {
;         f32x4 L0[4][4], L1[4][4]; const bool two = s + 1 < seg;
;         const int ua = u - seg + s, ub = two ? ua + 1 : ua;
;         const float dca = __expf(rb.tseg[ua * 4 + k]), dcb = __expf(rb.tseg[ub * 4 + k]);
;         {   const float* hp = rb.hseg + (size_t)ua * 32768 + tid * 4;
; #pragma unroll
;             for (int nt = 0; nt < 4; ++nt)
; #pragma unroll
;                 for (int pt = 0; pt < 4; ++pt) { LAUNDER_PTR(hp); L0[nt][pt] = *(const f32x4*)hp; hp += 2048; } }
;         if (two) { const float* hp = rb.hseg + (size_t)ub * 32768 + tid * 4;
; #pragma unroll
;             for (int nt = 0; nt < 4; ++nt)
; #pragma unroll
;                 for (int pt = 0; pt < 4; ++pt) { LAUNDER_PTR(hp); L1[nt][pt] = *(const f32x4*)hp; hp += 2048; } }
; #pragma unroll
;         for (int nt = 0; nt < 4; ++nt)
; #pragma unroll
;             for (int pt = 0; pt < 4; ++pt) { H[nt][pt] = H[nt][pt] * dca + L0[nt][pt]; if (two) H[nt][pt] = H[nt][pt] * dcb + L1[nt][pt]; } }
	s_or_b32 s2, s0, 2
	v_lshl_add_u32 v12, s2, 2, v189
	s_ashr_i32 s3, s2, 31
	v_ashrrev_i32_e32 v13, 31, v12
	s_lshl_b64 s[2:3], s[2:3], 17
	v_lshl_add_u64 v[12:13], v[12:13], 2, s[30:31]
	v_lshl_add_u64 v[8:9], v[8:9], 0, s[2:3]
	global_load_dword v10, v[12:13], off
	global_load_dwordx4 v[70:73], v[8:9], off nt
	v_lshl_add_u64 v[8:9], v[8:9], 0, s[44:45]
	global_load_dwordx4 v[74:77], v[8:9], off nt
	v_lshl_add_u64 v[8:9], v[8:9], 0, s[44:45]
	global_load_dwordx4 v[78:81], v[8:9], off nt
	v_lshl_add_u64 v[8:9], v[8:9], 0, s[44:45]
	global_load_dwordx4 v[82:85], v[8:9], off nt
	v_lshl_add_u64 v[8:9], v[8:9], 0, s[44:45]
	global_load_dwordx4 v[86:89], v[8:9], off nt
	v_lshl_add_u64 v[8:9], v[8:9], 0, s[44:45]
	global_load_dwordx4 v[90:93], v[8:9], off nt
	v_lshl_add_u64 v[8:9], v[8:9], 0, s[44:45]
	global_load_dwordx4 v[94:97], v[8:9], off nt
	v_lshl_add_u64 v[8:9], v[8:9], 0, s[44:45]
	global_load_dwordx4 v[98:101], v[8:9], off nt
	v_lshl_add_u64 v[8:9], v[8:9], 0, s[44:45]
	global_load_dwordx4 v[102:105], v[8:9], off nt
	v_lshl_add_u64 v[8:9], v[8:9], 0, s[44:45]
	global_load_dwordx4 v[106:109], v[8:9], off nt
	v_lshl_add_u64 v[8:9], v[8:9], 0, s[44:45]
	global_load_dwordx4 v[110:113], v[8:9], off nt
	v_lshl_add_u64 v[8:9], v[8:9], 0, s[44:45]
	global_load_dwordx4 v[114:117], v[8:9], off nt
	v_lshl_add_u64 v[8:9], v[8:9], 0, s[44:45]
	global_load_dwordx4 v[118:121], v[8:9], off nt
	v_lshl_add_u64 v[8:9], v[8:9], 0, s[44:45]
	global_load_dwordx4 v[122:125], v[8:9], off nt
	v_lshl_add_u64 v[8:9], v[8:9], 0, s[44:45]
	global_load_dwordx4 v[126:129], v[8:9], off nt
	v_lshl_add_u64 v[8:9], v[8:9], 0, s[44:45]
	global_load_dwordx4 v[130:133], v[8:9], off nt
	s_waitcnt vmcnt(0) lgkmcnt(0)
	v_mul_f32_e32 v8, 0x3fb8aa3b, v10
	v_exp_f32_e32 v8, v8
	s_nop 0
	v_pk_fma_f32 v[4:5], v[4:5], v[8:9], v[74:75] op_sel_hi:[1,0,1]
	v_pk_fma_f32 v[6:7], v[6:7], v[8:9], v[76:77] op_sel_hi:[1,0,1]
	v_pk_fma_f32 v[0:1], v[0:1], v[8:9], v[70:71] op_sel_hi:[1,0,1]
	v_pk_fma_f32 v[14:15], v[14:15], v[8:9], v[78:79] op_sel_hi:[1,0,1]
	v_pk_fma_f32 v[16:17], v[16:17], v[8:9], v[80:81] op_sel_hi:[1,0,1]
	v_pk_fma_f32 v[2:3], v[2:3], v[8:9], v[72:73] op_sel_hi:[1,0,1]
	v_pk_fma_f32 v[18:19], v[18:19], v[8:9], v[82:83] op_sel_hi:[1,0,1]
	v_pk_fma_f32 v[20:21], v[20:21], v[8:9], v[84:85] op_sel_hi:[1,0,1]
	v_pk_fma_f32 v[22:23], v[22:23], v[8:9], v[86:87] op_sel_hi:[1,0,1]
	v_pk_fma_f32 v[24:25], v[24:25], v[8:9], v[88:89] op_sel_hi:[1,0,1]
	v_pk_fma_f32 v[26:27], v[26:27], v[8:9], v[90:91] op_sel_hi:[1,0,1]
	v_pk_fma_f32 v[28:29], v[28:29], v[8:9], v[92:93] op_sel_hi:[1,0,1]
	v_pk_fma_f32 v[30:31], v[30:31], v[8:9], v[94:95] op_sel_hi:[1,0,1]
	v_pk_fma_f32 v[32:33], v[32:33], v[8:9], v[96:97] op_sel_hi:[1,0,1]
	v_pk_fma_f32 v[34:35], v[34:35], v[8:9], v[98:99] op_sel_hi:[1,0,1]
	v_pk_fma_f32 v[36:37], v[36:37], v[8:9], v[100:101] op_sel_hi:[1,0,1]
	v_pk_fma_f32 v[38:39], v[38:39], v[8:9], v[102:103] op_sel_hi:[1,0,1]
	v_pk_fma_f32 v[40:41], v[40:41], v[8:9], v[104:105] op_sel_hi:[1,0,1]
	v_pk_fma_f32 v[42:43], v[42:43], v[8:9], v[106:107] op_sel_hi:[1,0,1]
	v_pk_fma_f32 v[44:45], v[44:45], v[8:9], v[108:109] op_sel_hi:[1,0,1]
	v_pk_fma_f32 v[46:47], v[46:47], v[8:9], v[110:111] op_sel_hi:[1,0,1]
	v_pk_fma_f32 v[48:49], v[48:49], v[8:9], v[112:113] op_sel_hi:[1,0,1]
	v_pk_fma_f32 v[50:51], v[50:51], v[8:9], v[114:115] op_sel_hi:[1,0,1]
	v_pk_fma_f32 v[52:53], v[52:53], v[8:9], v[116:117] op_sel_hi:[1,0,1]
	v_pk_fma_f32 v[54:55], v[54:55], v[8:9], v[118:119] op_sel_hi:[1,0,1]
	v_pk_fma_f32 v[56:57], v[56:57], v[8:9], v[120:121] op_sel_hi:[1,0,1]
	v_pk_fma_f32 v[58:59], v[58:59], v[8:9], v[122:123] op_sel_hi:[1,0,1]
	v_pk_fma_f32 v[60:61], v[60:61], v[8:9], v[124:125] op_sel_hi:[1,0,1]
	v_pk_fma_f32 v[62:63], v[62:63], v[8:9], v[126:127] op_sel_hi:[1,0,1]
	v_pk_fma_f32 v[64:65], v[64:65], v[8:9], v[128:129] op_sel_hi:[1,0,1]
	v_pk_fma_f32 v[66:67], v[66:67], v[8:9], v[130:131] op_sel_hi:[1,0,1]
	v_pk_fma_f32 v[68:69], v[68:69], v[8:9], v[132:133] op_sel_hi:[1,0,1]
	s_branch .LBB0_856

; #define LAS __attribute__((address_space(3)))
; __device__ __forceinline__ void ssd_state_update(f32x4 (&H)[4][4], LAS unsigned char* Xi, int xp, LAS unsigned char* Bi, int bp, const LAS float* sDt, const LAS float* sCum, int w, int lane) {
;     const int g = lane >> 4, k = w >> 1, nh = w & 1;
;     const float tot = sCum[63 * 4 + k]; const float et = __expf(tot);
; #pragma unroll
;     for (int nt = 0; nt < 4; ++nt)
; #pragma unroll
;         for (int pt = 0; pt < 4; ++pt) H[nt][pt] = H[nt][pt] * et;
; #pragma unroll
;     for (int ks = 0; ks < 2; ++ks) {
;         float wg[8];
; #pragma unroll
;         for (int j = 0; j < 8; ++j) wg[j] = __expf(tot - sCum[(32 * ks + 8 * g + j) * 4 + k]) * sDt[(32 * ks + 8 * g + j) * 4 + k];
;         bf16x8 Bx[4];
; #pragma unroll
;         for (int pt = 0; pt < 4; ++pt) Bx[pt] = scale_frag8(frag_tr(Xi, xp, 32 * ks + 8 * g, 32 * ks + 8 * g + 4, 64 * k + 16 * pt, lane), wg);
.LBB0_865:
	ds_read_b32 v10, v131 offset:1008
	v_add_u32_e32 v155, v158, v159
	s_waitcnt lgkmcnt(0)
	v_mul_f32_e32 v12, 0x3fb8aa3b, v10
	v_exp_f32_e32 v102, v12
	s_nop 0
	v_pk_mul_f32 v[84:85], v[36:37], v[102:103] op_sel_hi:[1,0]
	ds_read_b32 v36, v134
	ds_read_b32 v37, v135
	v_pk_mul_f32 v[88:89], v[20:21], v[102:103] op_sel_hi:[1,0]
	v_pk_mul_f32 v[70:71], v[22:23], v[102:103] op_sel_hi:[1,0]
	v_pk_mul_f32 v[22:23], v[40:41], v[102:103] op_sel_hi:[1,0]
	v_pk_mul_f32 v[20:21], v[38:39], v[102:103] op_sel_hi:[1,0]
	ds_read_b32 v38, v138
	ds_read_b32 v40, v142
	s_waitcnt lgkmcnt(0)
	v_sub_f32_e32 v36, v10, v36
	v_mul_f32_e32 v36, 0x3fb8aa3b, v36
	v_exp_f32_e32 v36, v36
	v_pk_mul_f32 v[72:73], v[24:25], v[102:103] op_sel_hi:[1,0]
	v_pk_mul_f32 v[24:25], v[42:43], v[102:103] op_sel_hi:[1,0]
	ds_read_b32 v39, v140
	ds_read_b32 v42, v146
	v_mul_f32_e32 v36, v37, v36
	ds_read_b32 v37, v136
	v_pk_mul_f32 v[78:79], v[30:31], v[102:103] op_sel_hi:[1,0]
	v_pk_mul_f32 v[30:31], v[48:49], v[102:103] op_sel_hi:[1,0]
	v_pk_mul_f32 v[96:97], v[6:7], v[102:103] op_sel_hi:[1,0]
	v_pk_mul_f32 v[6:7], v[60:61], v[102:103] op_sel_hi:[1,0]
	s_waitcnt lgkmcnt(0)
	v_sub_f32_e32 v37, v10, v37
	v_mul_f32_e32 v37, 0x3fb8aa3b, v37
	v_exp_f32_e32 v37, v37
	ds_read_b32 v41, v144
	v_add_u32_e32 v60, v158, v133
	v_pk_mul_f32 v[98:99], v[0:1], v[102:103] op_sel_hi:[1,0]
	v_mul_f32_e32 v37, v38, v37
	ds_read_b32 v38, v139
	v_pk_mul_f32 v[74:75], v[26:27], v[102:103] op_sel_hi:[1,0]
	v_pk_mul_f32 v[82:83], v[34:35], v[102:103] op_sel_hi:[1,0]
	v_pk_mul_f32 v[26:27], v[44:45], v[102:103] op_sel_hi:[1,0]
	ds_read_b32 v43, v149
	s_waitcnt lgkmcnt(0)
	v_sub_f32_e32 v38, v10, v38
	v_mul_f32_e32 v38, 0x3fb8aa3b, v38
	v_exp_f32_e32 v38, v38
	v_pk_mul_f32 v[34:35], v[52:53], v[102:103] op_sel_hi:[1,0]
	v_pk_mul_f32 v[0:1], v[54:55], v[102:103] op_sel_hi:[1,0]
	v_pk_mul_f32 v[76:77], v[28:29], v[102:103] op_sel_hi:[1,0]
	v_mul_f32_e32 v38, v39, v38
	ds_read_b32 v39, v141
	v_pk_mul_f32 v[28:29], v[46:47], v[102:103] op_sel_hi:[1,0]
	v_pk_mul_f32 v[12:13], v[62:63], v[102:103] op_sel_hi:[1,0]
	v_pk_mul_f32 v[94:95], v[4:5], v[102:103] op_sel_hi:[1,0]
	v_pk_mul_f32 v[80:81], v[32:33], v[102:103] op_sel_hi:[1,0]
	s_waitcnt lgkmcnt(0)
	v_sub_f32_e32 v39, v10, v39
	v_mul_f32_e32 v39, 0x3fb8aa3b, v39
	v_exp_f32_e32 v39, v39
	v_pk_mul_f32 v[32:33], v[50:51], v[102:103] op_sel_hi:[1,0]
	v_pk_mul_f32 v[4:5], v[58:59], v[102:103] op_sel_hi:[1,0]
	v_pk_mul_f32 v[100:101], v[2:3], v[102:103] op_sel_hi:[1,0]
	v_mul_f32_e32 v39, v40, v39
	ds_read_b32 v40, v143
	v_pk_mul_f32 v[90:91], v[14:15], v[102:103] op_sel_hi:[1,0]
	v_pk_mul_f32 v[2:3], v[56:57], v[102:103] op_sel_hi:[1,0]
	v_pk_mul_f32 v[14:15], v[64:65], v[102:103] op_sel_hi:[1,0]
	v_pk_mul_f32 v[92:93], v[16:17], v[102:103] op_sel_hi:[1,0]
	s_waitcnt lgkmcnt(0)
	v_sub_f32_e32 v40, v10, v40
	v_mul_f32_e32 v40, 0x3fb8aa3b, v40
	v_exp_f32_e32 v40, v40
	v_pk_mul_f32 v[16:17], v[66:67], v[102:103] op_sel_hi:[1,0]
	v_pk_mul_f32 v[86:87], v[18:19], v[102:103] op_sel_hi:[1,0]
	v_pk_mul_f32 v[18:19], v[68:69], v[102:103] op_sel_hi:[1,0]
	v_mul_f32_e32 v40, v41, v40
	ds_read_b32 v41, v145
	s_waitcnt lgkmcnt(0)
	v_sub_f32_e32 v41, v10, v41
	v_mul_f32_e32 v41, 0x3fb8aa3b, v41
	v_exp_f32_e32 v41, v41
	s_nop 0
	v_mul_f32_e32 v42, v42, v41
	ds_read_b32 v41, v147
	s_waitcnt lgkmcnt(0)
	v_sub_f32_e32 v41, v10, v41
	v_mul_f32_e32 v41, 0x3fb8aa3b, v41
	v_exp_f32_e32 v41, v41
	s_nop 0
	v_mul_f32_e32 v48, v43, v41
	ds_read_b32 v41, v156
	ds_read_b32 v43, v157
	ds_read_b64_tr_b16 v[52:53], v60 offset:4160
	ds_read_b64_tr_b16 v[44:45], v60
	ds_read_b64_tr_b16 v[54:55], v60 offset:32
	ds_read_b64_tr_b16 v[62:63], v60 offset:4192
	s_waitcnt lgkmcnt(0)
	v_sub_f32_e32 v41, v10, v41
	v_mul_f32_e32 v41, 0x3fb8aa3b, v41
	v_exp_f32_e32 v41, v41
	v_and_b32_e32 v47, 0xffff0000, v52
	v_mul_f32_e32 v47, v42, v47
	v_cvt_pk_bf16_f32 v49, v47, v47
	v_lshlrev_b32_e32 v47, 16, v53
	v_mul_f32_e32 v47, v48, v47
	v_mul_f32_e32 v59, v43, v41
	v_cvt_pk_bf16_f32 v51, v47, v47
	v_and_b32_e32 v47, 0xffff0000, v53
	v_mul_f32_e32 v47, v59, v47
	v_lshlrev_b32_e32 v46, 16, v52
	v_cvt_pk_bf16_f32 v53, v47, v47
	v_lshlrev_b32_e32 v47, 16, v54
	v_and_b32_e32 v50, 0xffff0000, v54
	v_lshlrev_b32_e32 v52, 16, v55
	v_and_b32_e32 v54, 0xffff0000, v55
	v_lshlrev_b32_e32 v55, 16, v62
	v_and_b32_e32 v56, 0xffff0000, v62
	v_lshlrev_b32_e32 v57, 16, v63
	v_and_b32_e32 v58, 0xffff0000, v63
	ds_read_b64_tr_b16 v[62:63], v60 offset:64
	ds_read_b64_tr_b16 v[64:65], v60 offset:4224
	v_lshlrev_b32_e32 v41, 16, v44
	v_mul_f32_e32 v41, v36, v41
	v_mul_f32_e32 v47, v36, v47
	s_waitcnt lgkmcnt(0)
	v_lshlrev_b32_e32 v61, 16, v62
	v_mul_f32_e32 v61, v36, v61
	v_cvt_pk_bf16_f32 v66, v61, v61
	v_and_b32_e32 v61, 0xffff0000, v62
	v_mul_f32_e32 v61, v37, v61
	v_cvt_pk_bf16_f32 v67, v61, v61
	v_lshlrev_b32_e32 v61, 16, v63
	v_mul_f32_e32 v61, v38, v61
	v_cvt_pk_bf16_f32 v68, v61, v61
	v_and_b32_e32 v61, 0xffff0000, v63
	v_mul_f32_e32 v61, v39, v61
	v_cvt_pk_bf16_f32 v69, v61, v61
	v_lshlrev_b32_e32 v61, 16, v64
	v_mul_f32_e32 v61, v40, v61
	v_cvt_pk_bf16_f32 v102, v61, v61
	v_and_b32_e32 v61, 0xffff0000, v64
	v_mul_f32_e32 v61, v42, v61
	v_cvt_pk_bf16_f32 v64, v61, v61
	v_lshlrev_b32_e32 v61, 16, v65
	v_mul_f32_e32 v61, v48, v61
	v_cvt_pk_bf16_f32 v126, v61, v61
	v_and_b32_e32 v61, 0xffff0000, v65
	v_mul_f32_e32 v61, v59, v61
	v_cvt_pk_bf16_f32 v65, v61, v61
	ds_read_b64_tr_b16 v[62:63], v60 offset:96
	ds_read_b64_tr_b16 v[60:61], v60 offset:4256
	v_mul_f32_e32 v57, v48, v57
	v_and_b32_e32 v43, 0xffff0000, v44
	v_lshlrev_b32_e32 v44, 16, v45
	s_waitcnt lgkmcnt(0)
; __device__ __forceinline__ f32x4 mfma16(bf16x8 a, bf16x8 b, f32x4 c) { return __builtin_amdgcn_mfma_f32_16x16x32_bf16(a, b, c, 0, 0, 0); }
; #define SCHED_FENCE() do {} while (0)
; #define SCHED_FENCE() __builtin_amdgcn_sched_barrier(0)
; __device__ __forceinline__ void ssd_state_update(f32x4 (&H)[4][4], LAS unsigned char* Xi, int xp, LAS unsigned char* Bi, int bp, const LAS float* sDt, const LAS float* sCum, int w, int lane) {
;     ...
;     for (int ks = 0; ks < 2; ++ks) {
;         float wg[8];
; #pragma unroll
;         for (int j = 0; j < 8; ++j) wg[j] = __expf(tot - sCum[(32 * ks + 8 * g + j) * 4 + k]) * sDt[(32 * ks + 8 * g + j) * 4 + k];
;         bf16x8 Bx[4];
; #pragma unroll
;         for (int pt = 0; pt < 4; ++pt) Bx[pt] = scale_frag8(frag_tr(Xi, xp, 32 * ks + 8 * g, 32 * ks + 8 * g + 4, 64 * k + 16 * pt, lane), wg);
; #pragma unroll
;         for (int nt = 0; nt < 4; ++nt) { const bf16x8 A = frag_tr(Bi, bp, 32 * ks + 8 * g, 32 * ks + 8 * g + 4, 16 * (4 * nh + nt), lane);
; #pragma unroll
;             for (int pt = 0; pt < 4; ++pt) H[nt][pt] = mfma16(A, Bx[pt], H[nt][pt]);
;             SCHED_FENCE(); }
;     }
	v_lshlrev_b32_e32 v122, 16, v62
	v_mul_f32_e32 v36, v36, v122
	v_cvt_pk_bf16_f32 v127, v36, v36
	v_and_b32_e32 v36, 0xffff0000, v62
	v_mul_f32_e32 v36, v37, v36
	v_cvt_pk_bf16_f32 v150, v36, v36
	v_lshlrev_b32_e32 v36, 16, v63
	v_mul_f32_e32 v36, v38, v36
	v_cvt_pk_bf16_f32 v151, v36, v36
	v_and_b32_e32 v36, 0xffff0000, v63
	v_mul_f32_e32 v36, v39, v36
	v_cvt_pk_bf16_f32 v152, v36, v36
	v_lshlrev_b32_e32 v36, 16, v60
	v_mul_f32_e32 v36, v40, v36
	v_cvt_pk_bf16_f32 v153, v36, v36
	v_and_b32_e32 v36, 0xffff0000, v60
	v_mul_f32_e32 v36, v42, v36
	v_cvt_pk_bf16_f32 v154, v36, v36
	v_lshlrev_b32_e32 v36, 16, v61
	v_mul_f32_e32 v36, v48, v36
	v_cvt_pk_bf16_f32 v48, v36, v36
	v_and_b32_e32 v36, 0xffff0000, v61
	ds_read_b64_tr_b16 v[60:61], v155 offset:512
	ds_read_b64_tr_b16 v[62:63], v155 offset:4672
	v_and_b32_e32 v45, 0xffff0000, v45
	v_mul_f32_e32 v43, v37, v43
	v_mul_f32_e32 v44, v38, v44
	v_mul_f32_e32 v45, v39, v45
	v_mul_f32_e32 v46, v40, v46
	v_cvt_pk_bf16_f32 v41, v41, v41
	v_cvt_pk_bf16_f32 v43, v43, v43
	v_cvt_pk_bf16_f32 v44, v44, v44
	v_cvt_pk_bf16_f32 v45, v45, v45
	v_cvt_pk_bf16_f32 v46, v46, v46
	v_mul_f32_e32 v50, v37, v50
	v_mul_f32_e32 v52, v38, v52
	v_mul_f32_e32 v54, v39, v54
	v_mul_f32_e32 v55, v40, v55
	v_mul_f32_e32 v56, v42, v56
	v_mul_f32_e32 v58, v59, v58
	v_mul_f32_e32 v36, v59, v36
	v_perm_b32 v125, v53, v51, s75
	v_perm_b32 v124, v49, v46, s75
	v_perm_b32 v123, v45, v44, s75
	v_perm_b32 v122, v43, v41, s75
	v_cvt_pk_bf16_f32 v47, v47, v47
	v_cvt_pk_bf16_f32 v50, v50, v50
	v_cvt_pk_bf16_f32 v52, v52, v52
	v_cvt_pk_bf16_f32 v54, v54, v54
	v_cvt_pk_bf16_f32 v55, v55, v55
	v_cvt_pk_bf16_f32 v56, v56, v56
	v_cvt_pk_bf16_f32 v57, v57, v57
	v_cvt_pk_bf16_f32 v58, v58, v58
	v_cvt_pk_bf16_f32 v59, v36, v36
	s_waitcnt lgkmcnt(0)
	s_nop 0
	v_mfma_f32_16x16x32_bf16 v[36:39], v[60:63], v[122:125], v[98:101]
	v_perm_b32 v233, v59, v48, s75
	v_perm_b32 v232, v154, v153, s75
	v_perm_b32 v231, v152, v151, s75
	v_perm_b32 v101, v58, v57, s75
	v_perm_b32 v100, v56, v55, s75
	v_perm_b32 v99, v54, v52, s75
	v_perm_b32 v98, v50, v47, s75
	v_perm_b32 v230, v150, v127, s75
	s_nop 0
	v_mfma_f32_16x16x32_bf16 v[40:43], v[60:63], v[98:101], v[94:97]
	s_nop 2
	v_perm_b32 v97, v65, v126, s75
	v_perm_b32 v96, v64, v102, s75
	v_perm_b32 v95, v69, v68, s75
	v_perm_b32 v94, v67, v66, s75
	v_mfma_f32_16x16x32_bf16 v[48:51], v[60:63], v[230:233], v[86:89]
	s_nop 0
	v_mfma_f32_16x16x32_bf16 v[44:47], v[60:63], v[94:97], v[90:93]
	ds_read_b64_tr_b16 v[64:65], v155 offset:544
	ds_read_b64_tr_b16 v[66:67], v155 offset:4704
	s_waitcnt lgkmcnt(0)
	v_mfma_f32_16x16x32_bf16 v[52:55], v[64:67], v[122:125], v[70:73]
	v_mfma_f32_16x16x32_bf16 v[56:59], v[64:67], v[98:101], v[74:77]
	v_mfma_f32_16x16x32_bf16 v[60:63], v[64:67], v[94:97], v[78:81]
	v_mfma_f32_16x16x32_bf16 v[64:67], v[64:67], v[230:233], v[82:85]
	s_nop 1
	ds_read_b64_tr_b16 v[80:81], v155 offset:576
	ds_read_b64_tr_b16 v[82:83], v155 offset:4736
	s_waitcnt lgkmcnt(0)
	v_mfma_f32_16x16x32_bf16 v[68:71], v[80:83], v[122:125], v[20:23]
	v_mfma_f32_16x16x32_bf16 v[72:75], v[80:83], v[98:101], v[24:27]
	v_mfma_f32_16x16x32_bf16 v[76:79], v[80:83], v[94:97], v[28:31]
	v_mfma_f32_16x16x32_bf16 v[80:83], v[80:83], v[230:233], v[32:35]
	ds_read_b64_tr_b16 v[20:21], v155 offset:608
	ds_read_b64_tr_b16 v[22:23], v155 offset:4768
	s_waitcnt lgkmcnt(0)
	v_mfma_f32_16x16x32_bf16 v[84:87], v[20:23], v[122:125], v[0:3]
	v_mfma_f32_16x16x32_bf16 v[88:91], v[20:23], v[98:101], v[4:7]
	v_mfma_f32_16x16x32_bf16 v[92:95], v[20:23], v[94:97], v[12:15]
	v_mfma_f32_16x16x32_bf16 v[96:99], v[20:23], v[230:233], v[16:19]
	ds_read_b32 v0, v160
	ds_read_b32 v1, v161
	ds_read_b32 v2, v163
	ds_read_b32 v4, v167
	v_add_u32_e32 v32, v188, v133
	s_waitcnt lgkmcnt(0)
	v_sub_f32_e32 v0, v10, v0
	v_mul_f32_e32 v0, 0x3fb8aa3b, v0
	v_exp_f32_e32 v0, v0
	v_add_u32_e32 v177, v188, v159
	ds_read_b32 v3, v165
	ds_read_b32 v6, v171
	v_mul_f32_e32 v0, v1, v0
	ds_read_b32 v1, v162
	ds_read_b32 v5, v169
	ds_read_b32 v7, v173
	s_waitcnt lgkmcnt(0)
	v_sub_f32_e32 v1, v10, v1
	v_mul_f32_e32 v1, 0x3fb8aa3b, v1
	v_exp_f32_e32 v1, v1
	s_nop 0
	v_mul_f32_e32 v1, v2, v1
	ds_read_b32 v2, v164
	s_waitcnt lgkmcnt(0)
	v_sub_f32_e32 v2, v10, v2
	v_mul_f32_e32 v2, 0x3fb8aa3b, v2
	v_exp_f32_e32 v2, v2
	s_nop 0
	v_mul_f32_e32 v2, v3, v2
	ds_read_b32 v3, v166
	s_waitcnt lgkmcnt(0)
	v_sub_f32_e32 v3, v10, v3
	v_mul_f32_e32 v3, 0x3fb8aa3b, v3
	v_exp_f32_e32 v3, v3
	s_nop 0
	v_mul_f32_e32 v3, v4, v3
	ds_read_b32 v4, v168
	s_waitcnt lgkmcnt(0)
	v_sub_f32_e32 v4, v10, v4
	v_mul_f32_e32 v4, 0x3fb8aa3b, v4
	v_exp_f32_e32 v4, v4
	s_nop 0
	v_mul_f32_e32 v4, v5, v4
	ds_read_b32 v5, v170
	s_waitcnt lgkmcnt(0)
	v_sub_f32_e32 v5, v10, v5
	v_mul_f32_e32 v5, 0x3fb8aa3b, v5
	v_exp_f32_e32 v5, v5
	s_nop 0
	v_mul_f32_e32 v5, v6, v5
	ds_read_b32 v6, v172
	s_waitcnt lgkmcnt(0)
	v_sub_f32_e32 v6, v10, v6
	v_mul_f32_e32 v6, 0x3fb8aa3b, v6
	v_exp_f32_e32 v6, v6
	s_nop 0
	v_mul_f32_e32 v6, v7, v6
	ds_read_b32 v7, v174
	s_waitcnt lgkmcnt(0)
	v_sub_f32_e32 v7, v10, v7
	ds_read_b32 v10, v175
	ds_read_b64_tr_b16 v[20:21], v32 offset:4160
	ds_read_b64_tr_b16 v[12:13], v32
	ds_read_b64_tr_b16 v[22:23], v32 offset:32
	v_mul_f32_e32 v7, 0x3fb8aa3b, v7
	v_exp_f32_e32 v7, v7
	s_waitcnt lgkmcnt(0)
	v_and_b32_e32 v16, 0xffff0000, v20
	v_mul_f32_e32 v16, v5, v16
	ds_read_b64_tr_b16 v[26:27], v32 offset:4192
	v_cvt_pk_bf16_f32 v17, v16, v16
	v_lshlrev_b32_e32 v16, 16, v21
	ds_read_b64_tr_b16 v[28:29], v32 offset:64
	ds_read_b64_tr_b16 v[30:31], v32 offset:4224
	v_mul_f32_e32 v16, v6, v16
	v_mul_f32_e32 v14, v10, v7
	v_cvt_pk_bf16_f32 v19, v16, v16
	v_and_b32_e32 v16, 0xffff0000, v21
	v_mul_f32_e32 v16, v14, v16
	v_lshlrev_b32_e32 v15, 16, v20
	v_cvt_pk_bf16_f32 v21, v16, v16
	v_lshlrev_b32_e32 v16, 16, v22
	v_and_b32_e32 v18, 0xffff0000, v22
	v_lshlrev_b32_e32 v20, 16, v23
	v_and_b32_e32 v22, 0xffff0000, v23
	s_waitcnt lgkmcnt(0)
; __device__ __forceinline__ f32x4 mfma16(bf16x8 a, bf16x8 b, f32x4 c) { return __builtin_amdgcn_mfma_f32_16x16x32_bf16(a, b, c, 0, 0, 0); }
; __device__ __forceinline__ void sync_threads() { __syncthreads(); }
; #define SCHED_FENCE() do {} while (0)
; #define SCHED_FENCE() __builtin_amdgcn_sched_barrier(0)
; __device__ __forceinline__ void ssd_state_update(f32x4 (&H)[4][4], LAS unsigned char* Xi, int xp, LAS unsigned char* Bi, int bp, const LAS float* sDt, const LAS float* sCum, int w, int lane) {
;     ...
;     for (int ks = 0; ks < 2; ++ks) {
;         float wg[8];
; #pragma unroll
;         for (int j = 0; j < 8; ++j) wg[j] = __expf(tot - sCum[(32 * ks + 8 * g + j) * 4 + k]) * sDt[(32 * ks + 8 * g + j) * 4 + k];
;         bf16x8 Bx[4];
; #pragma unroll
;         for (int pt = 0; pt < 4; ++pt) Bx[pt] = scale_frag8(frag_tr(Xi, xp, 32 * ks + 8 * g, 32 * ks + 8 * g + 4, 64 * k + 16 * pt, lane), wg);
; #pragma unroll
;         for (int nt = 0; nt < 4; ++nt) { const bf16x8 A = frag_tr(Bi, bp, 32 * ks + 8 * g, 32 * ks + 8 * g + 4, 16 * (4 * nh + nt), lane);
; #pragma unroll
;             for (int pt = 0; pt < 4; ++pt) H[nt][pt] = mfma16(A, Bx[pt], H[nt][pt]);
;             SCHED_FENCE(); }
;     }
; }
; __device__ __forceinline__ void ssd_pass2(const RecurBufs& rb, const float* d_skip, const float* ssm_norm, float* state_out_l, int u, int tid, LAS unsigned char* lds) {
;     ...
;         sync_threads();
;         {   const f32x4 nw = *(const f32x4*)(ssm_norm + chn0);
;             unsigned long long yy[8];
;             const int itA = hf, itB = 3 - hf;
;             bf16* yb0 = rb.y + (row0 + 16 * itA + 4 * g) * 2048 + chn0;
	v_lshlrev_b32_e32 v23, 16, v26
	v_and_b32_e32 v24, 0xffff0000, v26
	v_lshlrev_b32_e32 v25, 16, v27
	v_and_b32_e32 v26, 0xffff0000, v27
	v_lshlrev_b32_e32 v27, 16, v28
	v_and_b32_e32 v28, 0xffff0000, v28
	v_mul_f32_e32 v28, v1, v28
	v_cvt_pk_bf16_f32 v33, v28, v28
	v_lshlrev_b32_e32 v28, 16, v29
	v_mul_f32_e32 v28, v2, v28
	v_cvt_pk_bf16_f32 v34, v28, v28
	v_and_b32_e32 v28, 0xffff0000, v29
	v_mul_f32_e32 v28, v3, v28
	v_cvt_pk_bf16_f32 v35, v28, v28
	v_lshlrev_b32_e32 v28, 16, v30
	v_mul_f32_e32 v28, v4, v28
	v_cvt_pk_bf16_f32 v100, v28, v28
	v_and_b32_e32 v28, 0xffff0000, v30
	v_mul_f32_e32 v28, v5, v28
	v_cvt_pk_bf16_f32 v101, v28, v28
	v_lshlrev_b32_e32 v28, 16, v31
	v_mul_f32_e32 v28, v6, v28
	v_cvt_pk_bf16_f32 v102, v28, v28
	v_and_b32_e32 v28, 0xffff0000, v31
	v_mul_f32_e32 v28, v14, v28
	v_cvt_pk_bf16_f32 v126, v28, v28
	ds_read_b64_tr_b16 v[28:29], v32 offset:96
	ds_read_b64_tr_b16 v[30:31], v32 offset:4256
	v_lshlrev_b32_e32 v7, 16, v12
	v_mul_f32_e32 v7, v0, v7
	v_mul_f32_e32 v16, v0, v16
	s_waitcnt lgkmcnt(0)
	v_lshlrev_b32_e32 v32, 16, v28
	v_mul_f32_e32 v27, v0, v27
	v_mul_f32_e32 v0, v0, v32
	v_cvt_pk_bf16_f32 v32, v0, v0
	v_and_b32_e32 v0, 0xffff0000, v28
	v_mul_f32_e32 v0, v1, v0
	v_cvt_pk_bf16_f32 v127, v0, v0
	v_lshlrev_b32_e32 v0, 16, v29
	v_mul_f32_e32 v0, v2, v0
	v_cvt_pk_bf16_f32 v150, v0, v0
	v_and_b32_e32 v0, 0xffff0000, v29
	v_mul_f32_e32 v0, v3, v0
	v_cvt_pk_bf16_f32 v151, v0, v0
	v_lshlrev_b32_e32 v0, 16, v30
	v_mul_f32_e32 v0, v4, v0
	v_cvt_pk_bf16_f32 v152, v0, v0
	v_and_b32_e32 v0, 0xffff0000, v30
	v_mul_f32_e32 v0, v5, v0
	v_cvt_pk_bf16_f32 v153, v0, v0
	v_lshlrev_b32_e32 v0, 16, v31
	v_mul_f32_e32 v0, v6, v0
	v_cvt_pk_bf16_f32 v154, v0, v0
	v_and_b32_e32 v0, 0xffff0000, v31
	ds_read_b64_tr_b16 v[28:29], v177 offset:512
	ds_read_b64_tr_b16 v[30:31], v177 offset:4672
	v_and_b32_e32 v10, 0xffff0000, v12
	v_lshlrev_b32_e32 v12, 16, v13
	v_and_b32_e32 v13, 0xffff0000, v13
	v_mul_f32_e32 v10, v1, v10
	v_mul_f32_e32 v12, v2, v12
	v_mul_f32_e32 v13, v3, v13
	v_mul_f32_e32 v15, v4, v15
	v_mul_f32_e32 v18, v1, v18
	v_mul_f32_e32 v20, v2, v20
	v_mul_f32_e32 v22, v3, v22
	v_mul_f32_e32 v23, v4, v23
	v_mul_f32_e32 v24, v5, v24
	v_mul_f32_e32 v25, v6, v25
	v_mul_f32_e32 v26, v14, v26
	v_cvt_pk_bf16_f32 v7, v7, v7
	v_cvt_pk_bf16_f32 v10, v10, v10
	v_cvt_pk_bf16_f32 v12, v12, v12
	v_cvt_pk_bf16_f32 v13, v13, v13
	v_cvt_pk_bf16_f32 v15, v15, v15
	v_cvt_pk_bf16_f32 v16, v16, v16
	v_cvt_pk_bf16_f32 v18, v18, v18
	v_cvt_pk_bf16_f32 v20, v20, v20
	v_cvt_pk_bf16_f32 v22, v22, v22
	v_cvt_pk_bf16_f32 v23, v23, v23
	v_cvt_pk_bf16_f32 v24, v24, v24
	v_cvt_pk_bf16_f32 v25, v25, v25
	v_cvt_pk_bf16_f32 v26, v26, v26
	v_cvt_pk_bf16_f32 v27, v27, v27
	v_mul_f32_e32 v0, v14, v0
	v_cvt_pk_bf16_f32 v155, v0, v0
	v_perm_b32 v125, v21, v19, s75
	v_perm_b32 v124, v17, v15, s75
	v_perm_b32 v123, v13, v12, s75
	v_perm_b32 v122, v10, v7, s75
	v_perm_b32 v233, v26, v25, s75
	v_perm_b32 v232, v24, v23, s75
	v_perm_b32 v231, v22, v20, s75
	v_perm_b32 v230, v18, v16, s75
	v_perm_b32 v237, v126, v102, s75
	v_perm_b32 v236, v101, v100, s75
	v_perm_b32 v235, v35, v34, s75
	v_perm_b32 v234, v33, v27, s75
	v_perm_b32 v241, v155, v154, s75
	v_perm_b32 v240, v153, v152, s75
	v_perm_b32 v239, v151, v150, s75
	v_perm_b32 v238, v127, v32, s75
	s_waitcnt lgkmcnt(0)
	v_mfma_f32_16x16x32_bf16 v[0:3], v[28:31], v[122:125], v[36:39]
	v_mfma_f32_16x16x32_bf16 v[4:7], v[28:31], v[230:233], v[40:43]
	v_mfma_f32_16x16x32_bf16 v[14:17], v[28:31], v[234:237], v[44:47]
	v_mfma_f32_16x16x32_bf16 v[18:21], v[28:31], v[238:241], v[48:51]
	ds_read_b64_tr_b16 v[34:35], v177 offset:544
	ds_read_b64_tr_b16 v[36:37], v177 offset:4704
	s_waitcnt lgkmcnt(0)
	v_mfma_f32_16x16x32_bf16 v[22:25], v[34:37], v[122:125], v[52:55]
	v_mfma_f32_16x16x32_bf16 v[26:29], v[34:37], v[230:233], v[56:59]
	v_mfma_f32_16x16x32_bf16 v[30:33], v[34:37], v[234:237], v[60:63]
	v_mfma_f32_16x16x32_bf16 v[34:37], v[34:37], v[238:241], v[64:67]
	ds_read_b64_tr_b16 v[50:51], v177 offset:576
	ds_read_b64_tr_b16 v[52:53], v177 offset:4736
	s_waitcnt lgkmcnt(0)
	v_mfma_f32_16x16x32_bf16 v[38:41], v[50:53], v[122:125], v[68:71]
	v_mfma_f32_16x16x32_bf16 v[42:45], v[50:53], v[230:233], v[72:75]
	v_mfma_f32_16x16x32_bf16 v[46:49], v[50:53], v[234:237], v[76:79]
	v_mfma_f32_16x16x32_bf16 v[50:53], v[50:53], v[238:241], v[80:83]
	ds_read_b64_tr_b16 v[66:67], v177 offset:608
	ds_read_b64_tr_b16 v[68:69], v177 offset:4768
	s_waitcnt lgkmcnt(0)
	v_mfma_f32_16x16x32_bf16 v[54:57], v[66:69], v[122:125], v[84:87]
	v_mfma_f32_16x16x32_bf16 v[58:61], v[66:69], v[230:233], v[88:91]
	v_mfma_f32_16x16x32_bf16 v[62:65], v[66:69], v[234:237], v[92:95]
	v_mfma_f32_16x16x32_bf16 v[66:69], v[66:69], v[238:241], v[96:99]
	v_mov_b32_e32 v13, s61
	v_or_b32_e32 v12, s60, v112
	v_lshlrev_b64 v[12:13], 12, v[12:13]
	v_lshl_add_u64 v[90:91], v[116:117], 0, v[12:13]
	v_mov_b64_e32 v[12:13], v[90:91]
	s_barrier
; __device__ __forceinline__ unsigned pk2(float lo, float hi) { unsigned r; asm("v_cvt_pk_bf16_f32 %0, %1, %2" : "=v"(r) : "v"(lo), "v"(hi)); return r; }
; #define LAUNDER_PTR(p) do {} while (0)
; #define LAUNDER_PTR(p) asm volatile("" : "+v"(p))
; __device__ __forceinline__ void ssd_pass2(const RecurBufs& rb, const float* d_skip, const float* ssm_norm, float* state_out_l, int u, int tid, LAS unsigned char* lds) {
;     ...
;         {   const f32x4 nw = *(const f32x4*)(ssm_norm + chn0);
;             unsigned long long yy[8];
;             const int itA = hf, itB = 3 - hf;
;             bf16* yb0 = rb.y + (row0 + 16 * itA + 4 * g) * 2048 + chn0;
;             const int jump = (16 * (itB - itA) - 3) * 2048;
;             {   bf16* yp = yb0;
; #pragma unroll
;                 for (int q = 0; q < 8; ++q) { LAUNDER_PTR(yp); yy[q] = *(const unsigned long long*)yp; yp += (q == 3) ? jump : 2048; } }
;             bf16* yp = yb0;
; #pragma unroll
;             for (int q = 0; q < 8; ++q) { const int i = 16 * (q < 4 ? itA : itB) + 4 * g + (q & 3);
;                 const float rstd = rsqrtf(((red[i * 4] + red[i * 4 + 1]) + (red[i * 4 + 2] + red[i * 4 + 3])) * (1.f / 256.f) + EPS);
;                 const unsigned lo = (unsigned)yy[q], hi = (unsigned)(yy[q] >> 32);
;                 const float y0 = __uint_as_float(lo << 16) * rstd * nw[0], y1 = __uint_as_float(lo & 0xffff0000u) * rstd * nw[1], y2 = __uint_as_float(hi << 16) * rstd * nw[2], y3 = __uint_as_float(hi & 0xffff0000u) * rstd * nw[3];
;                 LAUNDER_PTR(yp); *(unsigned long long*)yp = (unsigned long long)pk2(y0, y1) | ((unsigned long long)pk2(y2, y3) << 32); yp += (q == 3) ? jump : 2048; } }
	global_load_dwordx4 v[70:73], v[110:111], off nt
	global_load_dwordx2 v[92:93], v[12:13], off
	v_lshl_add_u64 v[12:13], v[12:13], 0, s[94:95]
	global_load_dwordx2 v[84:85], v[12:13], off
	v_lshl_add_u64 v[12:13], v[12:13], 0, s[94:95]
	global_load_dwordx2 v[82:83], v[12:13], off
	v_lshl_add_u64 v[12:13], v[12:13], 0, s[94:95]
	global_load_dwordx2 v[80:81], v[12:13], off
	v_lshl_add_u64 v[12:13], v[12:13], 0, v[120:121]
	global_load_dwordx2 v[78:79], v[12:13], off
	v_lshl_add_u64 v[12:13], v[12:13], 0, s[94:95]
	global_load_dwordx2 v[76:77], v[12:13], off
	v_lshl_add_u64 v[12:13], v[12:13], 0, s[94:95]
	global_load_dwordx2 v[74:75], v[12:13], off
	v_lshl_add_u64 v[12:13], v[12:13], 0, s[94:95]
	ds_read_b128 v[86:89], v226
	global_load_dwordx2 v[12:13], v[12:13], off
	s_add_i32 s62, s62, 1
	s_cmp_eq_u32 s62, 8
	s_waitcnt lgkmcnt(0)
	v_mov_b32_e32 v94, v87
	v_mov_b32_e32 v95, v88
	v_mov_b32_e32 v87, v89
	v_pk_add_f32 v[86:87], v[94:95], v[86:87]
	s_waitcnt vmcnt(0)
	v_lshlrev_b32_e32 v88, 16, v93
	v_add_f32_e32 v10, v86, v87
	v_fmamk_f32 v10, v10, 0x3b800000, v176
	v_cmp_gt_f32_e32 vcc, s33, v10
	v_mul_f32_e32 v86, 0x4b800000, v10
	v_and_b32_e32 v87, 0xffff0000, v92
	v_cndmask_b32_e32 v10, v10, v86, vcc
	v_rsq_f32_e32 v10, v10
	v_and_b32_e32 v89, 0xffff0000, v93
	v_mul_f32_e32 v86, 0x45800000, v10
	v_cndmask_b32_e32 v10, v10, v86, vcc
	v_lshlrev_b32_e32 v86, 16, v92
	v_mul_f32_e32 v86, v10, v86
	v_mul_f32_e32 v87, v10, v87
	v_mul_f32_e32 v86, v70, v86
	v_mul_f32_e32 v87, v71, v87
	v_mul_f32_e32 v88, v10, v88
	v_mul_f32_e32 v10, v10, v89
	v_mul_f32_e32 v88, v72, v88
	v_mul_f32_e32 v10, v73, v10
	v_cvt_pk_bf16_f32 v86, v86, v87
	v_cvt_pk_bf16_f32 v87, v88, v10
	global_store_dwordx2 v[90:91], v[86:87], off
	ds_read_b128 v[86:89], v226 offset:16
	v_lshl_add_u64 v[90:91], v[90:91], 0, s[94:95]
	s_waitcnt lgkmcnt(0)
	v_mov_b32_e32 v92, v87
	v_mov_b32_e32 v93, v88
	v_mov_b32_e32 v87, v89
	v_pk_add_f32 v[86:87], v[92:93], v[86:87]
	v_lshl_add_u64 v[88:89], v[90:91], 0, s[94:95]
	v_add_f32_e32 v10, v86, v87
	v_fmamk_f32 v10, v10, 0x3b800000, v176
	v_cmp_gt_f32_e32 vcc, s33, v10
	v_mul_f32_e32 v86, 0x4b800000, v10
	v_lshlrev_b32_e32 v87, 16, v85
	v_cndmask_b32_e32 v10, v10, v86, vcc
	v_rsq_f32_e32 v10, v10
	v_and_b32_e32 v85, 0xffff0000, v85
	v_mul_f32_e32 v86, 0x45800000, v10
	v_cndmask_b32_e32 v10, v10, v86, vcc
	v_lshlrev_b32_e32 v86, 16, v84
	v_and_b32_e32 v84, 0xffff0000, v84
	v_mul_f32_e32 v84, v10, v84
	v_mul_f32_e32 v86, v10, v86
	v_mul_f32_e32 v84, v71, v84
	v_mul_f32_e32 v87, v10, v87
	v_mul_f32_e32 v10, v10, v85
	v_mul_f32_e32 v86, v70, v86
	v_mul_f32_e32 v87, v72, v87
	v_mul_f32_e32 v10, v73, v10
	v_cvt_pk_bf16_f32 v84, v86, v84
	v_cvt_pk_bf16_f32 v85, v87, v10
	global_store_dwordx2 v[90:91], v[84:85], off
	ds_read_b128 v[84:87], v226 offset:32
	s_waitcnt lgkmcnt(0)
	v_mov_b32_e32 v90, v85
	v_mov_b32_e32 v91, v86
	v_mov_b32_e32 v85, v87
	v_pk_add_f32 v[84:85], v[90:91], v[84:85]
	v_lshl_add_u64 v[86:87], v[88:89], 0, s[94:95]
	v_add_f32_e32 v10, v84, v85
	v_fmamk_f32 v10, v10, 0x3b800000, v176
	v_cmp_gt_f32_e32 vcc, s33, v10
	v_mul_f32_e32 v84, 0x4b800000, v10
	v_lshlrev_b32_e32 v85, 16, v83
	v_cndmask_b32_e32 v10, v10, v84, vcc
	v_rsq_f32_e32 v10, v10
	v_and_b32_e32 v83, 0xffff0000, v83
	v_mul_f32_e32 v84, 0x45800000, v10
	v_cndmask_b32_e32 v10, v10, v84, vcc
	v_lshlrev_b32_e32 v84, 16, v82
	v_and_b32_e32 v82, 0xffff0000, v82
	v_mul_f32_e32 v82, v10, v82
	v_mul_f32_e32 v84, v10, v84
	v_mul_f32_e32 v82, v71, v82
	v_mul_f32_e32 v85, v10, v85
	v_mul_f32_e32 v10, v10, v83
	v_mul_f32_e32 v84, v70, v84
	v_mul_f32_e32 v85, v72, v85
	v_mul_f32_e32 v10, v73, v10
	v_cvt_pk_bf16_f32 v82, v84, v82
	v_cvt_pk_bf16_f32 v83, v85, v10
	global_store_dwordx2 v[88:89], v[82:83], off
	ds_read_b128 v[82:85], v226 offset:48
	s_waitcnt lgkmcnt(0)
	v_mov_b32_e32 v88, v83
	v_mov_b32_e32 v89, v84
	v_mov_b32_e32 v83, v85
	v_pk_add_f32 v[82:83], v[88:89], v[82:83]
	v_lshl_add_u64 v[84:85], v[86:87], 0, v[120:121]
	v_add_f32_e32 v10, v82, v83
	v_fmamk_f32 v10, v10, 0x3b800000, v176
	v_cmp_gt_f32_e32 vcc, s33, v10
	v_mul_f32_e32 v82, 0x4b800000, v10
	v_lshlrev_b32_e32 v83, 16, v81
	v_cndmask_b32_e32 v10, v10, v82, vcc
	v_rsq_f32_e32 v10, v10
	v_and_b32_e32 v81, 0xffff0000, v81
	v_mul_f32_e32 v82, 0x45800000, v10
	v_cndmask_b32_e32 v10, v10, v82, vcc
	v_lshlrev_b32_e32 v82, 16, v80
	v_and_b32_e32 v80, 0xffff0000, v80
	v_mul_f32_e32 v80, v10, v80
	v_mul_f32_e32 v82, v10, v82
	v_mul_f32_e32 v80, v71, v80
	v_mul_f32_e32 v83, v10, v83
	v_mul_f32_e32 v10, v10, v81
	v_mul_f32_e32 v82, v70, v82
	v_mul_f32_e32 v83, v72, v83
	v_mul_f32_e32 v10, v73, v10
	v_cvt_pk_bf16_f32 v80, v82, v80
	v_cvt_pk_bf16_f32 v81, v83, v10
	global_store_dwordx2 v[86:87], v[80:81], off
	ds_read_b128 v[80:83], v227
	s_waitcnt lgkmcnt(0)
; __device__ __forceinline__ unsigned pk2(float lo, float hi) { unsigned r; asm("v_cvt_pk_bf16_f32 %0, %1, %2" : "=v"(r) : "v"(lo), "v"(hi)); return r; }
; __device__ __forceinline__ void sync_threads() { __syncthreads(); }
; #define LAUNDER_PTR(p) do {} while (0)
; #define LAUNDER_PTR(p) asm volatile("" : "+v"(p))
; __device__ __forceinline__ void ssd_pass2(const RecurBufs& rb, const float* d_skip, const float* ssm_norm, float* state_out_l, int u, int tid, LAS unsigned char* lds) {
;     ...
;     for (int ch = 0; ch < NCH; ++ch) {
;         const size_t row0 = rowS + ch * RC;
;         {   v4u raw[8];
;             {   const bf16* gp = rb.xbcc + (row0 + rr) * 4096 + gcol;
; #pragma unroll
;                 for (int i = 0; i < 8; ++i) { LAUNDER_PTR(gp); raw[i] = *(const v4u*)gp; gp += 8 * 4096; } }
;             if (tid < 256) { sDt[tid] = rb.dtv[(row0 + (tid >> 2)) * 32 + grp * 4 + (tid & 3)]; sCum[tid] = rb.cum[(row0 + (tid >> 2)) * 32 + grp * 4 + (tid & 3)]; }
;     ...
;             bf16* yp = yb0;
; #pragma unroll
;             for (int q = 0; q < 8; ++q) { const int i = 16 * (q < 4 ? itA : itB) + 4 * g + (q & 3);
;                 const float rstd = rsqrtf(((red[i * 4] + red[i * 4 + 1]) + (red[i * 4 + 2] + red[i * 4 + 3])) * (1.f / 256.f) + EPS);
;                 const unsigned lo = (unsigned)yy[q], hi = (unsigned)(yy[q] >> 32);
;                 const float y0 = __uint_as_float(lo << 16) * rstd * nw[0], y1 = __uint_as_float(lo & 0xffff0000u) * rstd * nw[1], y2 = __uint_as_float(hi << 16) * rstd * nw[2], y3 = __uint_as_float(hi & 0xffff0000u) * rstd * nw[3];
;                 LAUNDER_PTR(yp); *(unsigned long long*)yp = (unsigned long long)pk2(y0, y1) | ((unsigned long long)pk2(y2, y3) << 32); yp += (q == 3) ? jump : 2048; } }
;         sync_threads();
	v_mov_b32_e32 v86, v81
	v_mov_b32_e32 v87, v82
	v_mov_b32_e32 v81, v83
	v_pk_add_f32 v[80:81], v[86:87], v[80:81]
	v_lshl_add_u64 v[82:83], v[84:85], 0, s[94:95]
	v_add_f32_e32 v10, v80, v81
	v_fmamk_f32 v10, v10, 0x3b800000, v176
	v_cmp_gt_f32_e32 vcc, s33, v10
	v_mul_f32_e32 v80, 0x4b800000, v10
	v_lshlrev_b32_e32 v81, 16, v79
	v_cndmask_b32_e32 v10, v10, v80, vcc
	v_rsq_f32_e32 v10, v10
	v_and_b32_e32 v79, 0xffff0000, v79
	v_mul_f32_e32 v80, 0x45800000, v10
	v_cndmask_b32_e32 v10, v10, v80, vcc
	v_lshlrev_b32_e32 v80, 16, v78
	v_and_b32_e32 v78, 0xffff0000, v78
	v_mul_f32_e32 v78, v10, v78
	v_mul_f32_e32 v80, v10, v80
	v_mul_f32_e32 v78, v71, v78
	v_mul_f32_e32 v81, v10, v81
	v_mul_f32_e32 v10, v10, v79
	v_mul_f32_e32 v80, v70, v80
	v_mul_f32_e32 v81, v72, v81
	v_mul_f32_e32 v10, v73, v10
	v_cvt_pk_bf16_f32 v78, v80, v78
	v_cvt_pk_bf16_f32 v79, v81, v10
	global_store_dwordx2 v[84:85], v[78:79], off
	ds_read_b128 v[78:81], v227 offset:16
	s_waitcnt lgkmcnt(0)
	v_mov_b32_e32 v84, v79
	v_mov_b32_e32 v85, v80
	v_mov_b32_e32 v79, v81
	v_pk_add_f32 v[78:79], v[84:85], v[78:79]
	v_lshl_add_u64 v[80:81], v[82:83], 0, s[94:95]
	v_add_f32_e32 v10, v78, v79
	v_fmamk_f32 v10, v10, 0x3b800000, v176
	v_cmp_gt_f32_e32 vcc, s33, v10
	v_mul_f32_e32 v78, 0x4b800000, v10
	v_lshlrev_b32_e32 v79, 16, v77
	v_cndmask_b32_e32 v10, v10, v78, vcc
	v_rsq_f32_e32 v10, v10
	v_and_b32_e32 v77, 0xffff0000, v77
	v_mul_f32_e32 v78, 0x45800000, v10
	v_cndmask_b32_e32 v10, v10, v78, vcc
	v_lshlrev_b32_e32 v78, 16, v76
	v_and_b32_e32 v76, 0xffff0000, v76
	v_mul_f32_e32 v76, v10, v76
	v_mul_f32_e32 v78, v10, v78
	v_mul_f32_e32 v76, v71, v76
	v_mul_f32_e32 v79, v10, v79
	v_mul_f32_e32 v10, v10, v77
	v_mul_f32_e32 v78, v70, v78
	v_mul_f32_e32 v79, v72, v79
	v_mul_f32_e32 v10, v73, v10
	v_cvt_pk_bf16_f32 v76, v78, v76
	v_cvt_pk_bf16_f32 v77, v79, v10
	global_store_dwordx2 v[82:83], v[76:77], off
	ds_read_b128 v[76:79], v227 offset:32
	s_waitcnt lgkmcnt(0)
	v_mov_b32_e32 v82, v77
	v_mov_b32_e32 v83, v78
	v_mov_b32_e32 v77, v79
	v_pk_add_f32 v[76:77], v[82:83], v[76:77]
	v_lshl_add_u64 v[78:79], v[80:81], 0, s[94:95]
	v_add_f32_e32 v10, v76, v77
	v_fmamk_f32 v10, v10, 0x3b800000, v176
	v_cmp_gt_f32_e32 vcc, s33, v10
	v_mul_f32_e32 v76, 0x4b800000, v10
	v_lshlrev_b32_e32 v77, 16, v75
	v_cndmask_b32_e32 v10, v10, v76, vcc
	v_rsq_f32_e32 v10, v10
	v_and_b32_e32 v75, 0xffff0000, v75
	v_mul_f32_e32 v76, 0x45800000, v10
	v_cndmask_b32_e32 v10, v10, v76, vcc
	v_lshlrev_b32_e32 v76, 16, v74
	v_and_b32_e32 v74, 0xffff0000, v74
	v_mul_f32_e32 v74, v10, v74
	v_mul_f32_e32 v76, v10, v76
	v_mul_f32_e32 v74, v71, v74
	v_mul_f32_e32 v77, v10, v77
	v_mul_f32_e32 v10, v10, v75
	v_mul_f32_e32 v76, v70, v76
	v_mul_f32_e32 v77, v72, v77
	v_mul_f32_e32 v10, v73, v10
	v_cvt_pk_bf16_f32 v74, v76, v74
	v_cvt_pk_bf16_f32 v75, v77, v10
	global_store_dwordx2 v[80:81], v[74:75], off
	ds_read_b128 v[74:77], v227 offset:48
	s_waitcnt lgkmcnt(0)
	v_mov_b32_e32 v80, v75
	v_mov_b32_e32 v81, v76
	v_mov_b32_e32 v75, v77
	v_pk_add_f32 v[74:75], v[80:81], v[74:75]
	s_nop 0
	v_add_f32_e32 v10, v74, v75
	v_fmamk_f32 v10, v10, 0x3b800000, v176
	v_cmp_gt_f32_e32 vcc, s33, v10
	v_mul_f32_e32 v74, 0x4b800000, v10
	s_nop 0
	v_cndmask_b32_e32 v10, v10, v74, vcc
	v_rsq_f32_e32 v10, v10
	s_nop 0
	v_mul_f32_e32 v74, 0x45800000, v10
	v_cndmask_b32_e32 v10, v10, v74, vcc
	v_lshlrev_b32_e32 v74, 16, v12
	v_and_b32_e32 v12, 0xffff0000, v12
	v_mul_f32_e32 v12, v10, v12
	v_mul_f32_e32 v12, v71, v12
	v_lshlrev_b32_e32 v71, 16, v13
	v_and_b32_e32 v13, 0xffff0000, v13
	v_mul_f32_e32 v74, v10, v74
	v_mul_f32_e32 v71, v10, v71
	v_mul_f32_e32 v10, v10, v13
	v_mul_f32_e32 v70, v70, v74
	v_mul_f32_e32 v71, v72, v71
	v_mul_f32_e32 v10, v73, v10
	v_cvt_pk_bf16_f32 v12, v70, v12
	v_cvt_pk_bf16_f32 v13, v71, v10
	global_store_dwordx2 v[78:79], v[12:13], off
	s_waitcnt lgkmcnt(0)
	s_barrier
	s_cbranch_scc1 .LBB0_848
.LBB0_866:
	s_lshl_b32 s2, s62, 6
	s_add_u32 s60, s36, s2
	s_addc_u32 s61, s37, 0
	v_lshl_add_u64 v[12:13], s[60:61], 0, v[104:105]
	v_lshlrev_b64 v[12:13], 13, v[12:13]
	v_lshl_add_u64 v[12:13], v[114:115], 0, v[12:13]
	global_load_dwordx4 v[70:73], v[12:13], off nt
	v_lshl_add_u64 v[12:13], v[12:13], 0, s[42:43]
	global_load_dwordx4 v[74:77], v[12:13], off nt
	v_lshl_add_u64 v[12:13], v[12:13], 0, s[42:43]
	global_load_dwordx4 v[78:81], v[12:13], off nt
	v_lshl_add_u64 v[12:13], v[12:13], 0, s[42:43]
	global_load_dwordx4 v[82:85], v[12:13], off nt
	v_lshl_add_u64 v[12:13], v[12:13], 0, s[42:43]
	global_load_dwordx4 v[86:89], v[12:13], off nt
	v_lshl_add_u64 v[12:13], v[12:13], 0, s[42:43]
	global_load_dwordx4 v[90:93], v[12:13], off nt
	v_lshl_add_u64 v[12:13], v[12:13], 0, s[42:43]
	global_load_dwordx4 v[94:97], v[12:13], off nt
	v_lshl_add_u64 v[12:13], v[12:13], 0, s[42:43]
	global_load_dwordx4 v[98:101], v[12:13], off nt
	s_and_saveexec_b64 s[2:3], s[4:5]
	s_cbranch_execz .LBB0_868
	v_lshl_add_u64 v[12:13], s[60:61], 0, v[106:107]
	v_lshlrev_b64 v[12:13], 7, v[12:13]
	v_lshl_or_b32 v12, v108, 2, v12
	v_lshl_add_u64 v[122:123], s[22:23], 0, v[12:13]
	global_load_dword v10, v[122:123], off
	v_lshl_add_u64 v[12:13], s[24:25], 0, v[12:13]
	s_waitcnt vmcnt(0) lgkmcnt(0)
	ds_write_b32 v128, v10
	global_load_dword v10, v[12:13], off
	s_waitcnt vmcnt(0) lgkmcnt(0)
	ds_write_b32 v129, v10
